# GEMM loops: per-segment s_setprio toggling removed; one static priority raise for the trailing half-workgroup (waves 4-7) per tile
# speedup vs baseline: 1.0032x; 1.0032x over previous
.LBB0_191:
	s_ashr_i32 s9, s8, 31
	s_lshl_b64 s[10:11], s[8:9], 20
	s_add_u32 s10, s66, s10
	s_addc_u32 s11, s67, s11
	s_and_b64 s[12:13], s[0:1], exec
	s_cselect_b32 s9, s11, s15
	s_cselect_b32 s30, s10, s14
	s_ashr_i32 s7, s6, 31
	s_lshl_b64 s[12:13], s[6:7], 20
	s_add_u32 s12, s50, s12
	s_addc_u32 s13, s51, s13
	s_and_b64 s[18:19], s[0:1], exec
	s_cselect_b32 s7, s13, s17
	s_cselect_b32 s31, s12, s16
	s_add_u32 s33, s16, 0x100
	s_addc_u32 s34, s17, 0
	s_add_u32 s14, s14, 0x80080
	v_mov_b32_e32 v0, 0
	s_addc_u32 s15, s15, 0
	s_mov_b32 s35, -2
	v_mov_b32_e32 v1, v0
	v_mov_b32_e32 v2, v0
	v_mov_b32_e32 v3, v0
	v_mov_b32_e32 v4, v0
	v_mov_b32_e32 v5, v0
	v_mov_b32_e32 v6, v0
	v_mov_b32_e32 v7, v0
	v_mov_b32_e32 v8, v0
	v_mov_b32_e32 v9, v0
	v_mov_b32_e32 v10, v0
	v_mov_b32_e32 v11, v0
	v_mov_b32_e32 v16, v0
	v_mov_b32_e32 v17, v0
	v_mov_b32_e32 v18, v0
	v_mov_b32_e32 v19, v0
	v_mov_b32_e32 v24, v0
	v_mov_b32_e32 v25, v0
	v_mov_b32_e32 v26, v0
	v_mov_b32_e32 v27, v0
	v_mov_b32_e32 v32, v0
	v_mov_b32_e32 v33, v0
	v_mov_b32_e32 v34, v0
	v_mov_b32_e32 v35, v0
	v_mov_b32_e32 v40, v0
	v_mov_b32_e32 v41, v0
	v_mov_b32_e32 v42, v0
	v_mov_b32_e32 v43, v0
	v_mov_b32_e32 v48, v0
	v_mov_b32_e32 v49, v0
	v_mov_b32_e32 v50, v0
	v_mov_b32_e32 v51, v0
	v_mov_b32_e32 v12, v0
	v_mov_b32_e32 v13, v0
	v_mov_b32_e32 v14, v0
	v_mov_b32_e32 v15, v0
	v_mov_b32_e32 v20, v0
	v_mov_b32_e32 v21, v0
	v_mov_b32_e32 v22, v0
	v_mov_b32_e32 v23, v0
	v_mov_b32_e32 v28, v0
	v_mov_b32_e32 v29, v0
	v_mov_b32_e32 v30, v0
	v_mov_b32_e32 v31, v0
	v_mov_b32_e32 v36, v0
	v_mov_b32_e32 v37, v0
	v_mov_b32_e32 v38, v0
	v_mov_b32_e32 v39, v0
	v_mov_b32_e32 v44, v0
	v_mov_b32_e32 v45, v0
	v_mov_b32_e32 v46, v0
	v_mov_b32_e32 v47, v0
	v_mov_b32_e32 v52, v0
	v_mov_b32_e32 v53, v0
	v_mov_b32_e32 v54, v0
	v_mov_b32_e32 v55, v0
	v_mov_b32_e32 v56, v0
	v_mov_b32_e32 v57, v0
	v_mov_b32_e32 v58, v0
	v_mov_b32_e32 v59, v0
	v_mov_b32_e32 v60, v0
	v_mov_b32_e32 v61, v0
	v_mov_b32_e32 v62, v0
	v_mov_b32_e32 v63, v0
	v_mov_b32_e32 v64, v0
	v_mov_b32_e32 v65, v0
	v_mov_b32_e32 v66, v0
	v_mov_b32_e32 v67, v0
	v_mov_b32_e32 v68, v0
	v_mov_b32_e32 v69, v0
	v_mov_b32_e32 v70, v0
	v_mov_b32_e32 v71, v0
	v_mov_b32_e32 v72, v0
	v_mov_b32_e32 v73, v0
	v_mov_b32_e32 v74, v0
	v_mov_b32_e32 v75, v0
	v_mov_b32_e32 v80, v0
	v_mov_b32_e32 v81, v0
	v_mov_b32_e32 v82, v0
	v_mov_b32_e32 v83, v0
	v_mov_b32_e32 v88, v0
	v_mov_b32_e32 v89, v0
	v_mov_b32_e32 v90, v0
	v_mov_b32_e32 v91, v0
	v_mov_b32_e32 v96, v0
	v_mov_b32_e32 v97, v0
	v_mov_b32_e32 v98, v0
	v_mov_b32_e32 v99, v0
	v_mov_b32_e32 v104, v0
	v_mov_b32_e32 v105, v0
	v_mov_b32_e32 v106, v0
	v_mov_b32_e32 v107, v0
	v_mov_b32_e32 v112, v0
	v_mov_b32_e32 v113, v0
	v_mov_b32_e32 v114, v0
	v_mov_b32_e32 v115, v0
	v_mov_b32_e32 v76, v0
	v_mov_b32_e32 v77, v0
	v_mov_b32_e32 v78, v0
	v_mov_b32_e32 v79, v0
	v_mov_b32_e32 v84, v0
	v_mov_b32_e32 v85, v0
	v_mov_b32_e32 v86, v0
	v_mov_b32_e32 v87, v0
	v_mov_b32_e32 v92, v0
	v_mov_b32_e32 v93, v0
	v_mov_b32_e32 v94, v0
	v_mov_b32_e32 v95, v0
	v_mov_b32_e32 v100, v0
	v_mov_b32_e32 v101, v0
	v_mov_b32_e32 v102, v0
	v_mov_b32_e32 v103, v0
	v_mov_b32_e32 v108, v0
	v_mov_b32_e32 v109, v0
	v_mov_b32_e32 v110, v0
	v_mov_b32_e32 v111, v0
	v_mov_b32_e32 v116, v0
	v_mov_b32_e32 v117, v0
	v_mov_b32_e32 v118, v0
	v_mov_b32_e32 v119, v0
	v_mov_b32_e32 v120, v0
	v_mov_b32_e32 v121, v0
	v_mov_b32_e32 v122, v0
	v_mov_b32_e32 v123, v0
	v_mov_b32_e32 v124, v0
	v_mov_b32_e32 v125, v0
	v_mov_b32_e32 v126, v0
	v_mov_b32_e32 v127, v0
	s_mov_b64 s[74:75], 0x80
	v_add_u32_e32 v234, 0x10000, v143
	v_add_u32_e32 v235, 0x14000, v143
	v_add_u32_e32 v236, 0x18000, v143
	v_add_u32_e32 v237, 0x1c000, v143
	s_cmpk_ge_u32 s47, 0x100
	s_cbranch_scc0 .Lmy_pr_0
	s_setprio 1
.Lmy_pr_0:
.LBB0_192:
	s_add_u32 s98, s14, 0xfff80000
	s_addc_u32 s99, s15, -1
	s_mov_b32 m0, s25
	s_nop 0
	global_load_lds_dwordx4 v136, s[98:99]
	s_mov_b32 m0, s26
	s_nop 0
	global_load_lds_dwordx4 v134, s[98:99]
	s_add_u32 s16, s14, 0xfff80080
	s_addc_u32 s17, s15, -1
	s_add_i32 s36, 0, 0x10000
	s_cmp_eq_u32 s35, 28
	s_cselect_b32 s19, s9, s17
	s_cselect_b32 s18, s30, s16
	s_cselect_b32 s17, s7, s34
	s_cselect_b32 s16, s31, s33
	s_add_i32 s38, 0, 0x14000
	ds_read_b128 v[138:141], v234
	ds_read_b128 v[146:149], v234 offset:1024
	ds_read_b128 v[162:165], v234 offset:2048
	ds_read_b128 v[166:169], v234 offset:3072
	ds_read_b128 v[170:173], v235
	ds_read_b128 v[174:177], v235 offset:1024
	ds_read_b128 v[178:181], v235 offset:2048
	ds_read_b128 v[182:185], v235 offset:3072
	s_add_i32 m0, s21, 0xc000
	ds_read_b128 v[186:189], v145
	ds_read_b128 v[190:193], v145 offset:1024
	ds_read_b128 v[194:197], v145 offset:2048
	ds_read_b128 v[198:201], v145 offset:3072
	ds_read_b128 v[202:205], v145 offset:4096
	ds_read_b128 v[214:217], v145 offset:5120
	ds_read_b128 v[218:221], v145 offset:6144
	ds_read_b128 v[222:225], v145 offset:7168
	global_load_lds_dwordx4 v136, s[14:15]
	s_add_i32 m0, s21, 0xe000
	s_nop 0
	global_load_lds_dwordx4 v134, s[14:15]
	s_waitcnt vmcnt(8)
	s_waitcnt lgkmcnt(0)
	s_barrier
	s_waitcnt lgkmcnt(0)
	v_mfma_f32_16x16x32_bf16 v[124:127], v[138:141], v[186:189], v[124:127]
	v_mfma_f32_16x16x32_bf16 v[120:123], v[162:165], v[186:189], v[120:123]
	v_mfma_f32_16x16x32_bf16 v[116:119], v[138:141], v[194:197], v[116:119]
	v_mfma_f32_16x16x32_bf16 v[108:111], v[162:165], v[194:197], v[108:111]
	v_mfma_f32_16x16x32_bf16 v[100:103], v[138:141], v[202:205], v[100:103]
	v_mfma_f32_16x16x32_bf16 v[92:95], v[162:165], v[202:205], v[92:95]
	v_mfma_f32_16x16x32_bf16 v[84:87], v[138:141], v[218:221], v[84:87]
	v_mfma_f32_16x16x32_bf16 v[76:79], v[162:165], v[218:221], v[76:79]
	v_mfma_f32_16x16x32_bf16 v[124:127], v[146:149], v[190:193], v[124:127]
	v_mfma_f32_16x16x32_bf16 v[120:123], v[166:169], v[190:193], v[120:123]
	v_mfma_f32_16x16x32_bf16 v[116:119], v[146:149], v[198:201], v[116:119]
	v_mfma_f32_16x16x32_bf16 v[108:111], v[166:169], v[198:201], v[108:111]
	v_mfma_f32_16x16x32_bf16 v[100:103], v[146:149], v[214:217], v[100:103]
	v_mfma_f32_16x16x32_bf16 v[92:95], v[166:169], v[214:217], v[92:95]
	v_mfma_f32_16x16x32_bf16 v[84:87], v[146:149], v[222:225], v[84:87]
	v_mfma_f32_16x16x32_bf16 v[76:79], v[166:169], v[222:225], v[76:79]
	v_mfma_f32_16x16x32_bf16 v[112:115], v[170:173], v[186:189], v[112:115]
	v_mfma_f32_16x16x32_bf16 v[104:107], v[178:181], v[186:189], v[104:107]
	v_mfma_f32_16x16x32_bf16 v[96:99], v[170:173], v[194:197], v[96:99]
	v_mfma_f32_16x16x32_bf16 v[88:91], v[178:181], v[194:197], v[88:91]
	v_mfma_f32_16x16x32_bf16 v[80:83], v[170:173], v[202:205], v[80:83]
	v_mfma_f32_16x16x32_bf16 v[72:75], v[178:181], v[202:205], v[72:75]
	v_mfma_f32_16x16x32_bf16 v[68:71], v[170:173], v[218:221], v[68:71]
	v_mfma_f32_16x16x32_bf16 v[64:67], v[178:181], v[218:221], v[64:67]
	v_mfma_f32_16x16x32_bf16 v[112:115], v[174:177], v[190:193], v[112:115]
	v_mfma_f32_16x16x32_bf16 v[104:107], v[182:185], v[190:193], v[104:107]
	v_mfma_f32_16x16x32_bf16 v[96:99], v[174:177], v[198:201], v[96:99]
	v_mfma_f32_16x16x32_bf16 v[88:91], v[182:185], v[198:201], v[88:91]
	v_mfma_f32_16x16x32_bf16 v[80:83], v[174:177], v[214:217], v[80:83]
	v_mfma_f32_16x16x32_bf16 v[72:75], v[182:185], v[214:217], v[72:75]
	v_mfma_f32_16x16x32_bf16 v[68:71], v[174:177], v[222:225], v[68:71]
	v_mfma_f32_16x16x32_bf16 v[64:67], v[182:185], v[222:225], v[64:67]
	s_barrier
	s_add_i32 s36, s36, s20
	s_add_u32 s100, s16, 0x80
	s_addc_u32 s101, s17, 0
	s_mov_b32 m0, s36
	ds_read_b128 v[186:189], v145 offset:16384
	ds_read_b128 v[190:193], v145 offset:17408
	ds_read_b128 v[194:197], v145 offset:18432
	ds_read_b128 v[198:201], v145 offset:19456
	ds_read_b128 v[202:205], v145 offset:20480
	ds_read_b128 v[214:217], v145 offset:21504
	ds_read_b128 v[218:221], v145 offset:22528
	ds_read_b128 v[222:225], v145 offset:23552
	global_load_lds_dwordx4 v152, s[16:17]
	s_add_i32 m0, s36, 0x2000
	s_add_u32 s36, s16, 0x80000
	s_addc_u32 s37, s17, 0
	s_add_i32 s38, s38, s20
	global_load_lds_dwordx4 v128, s[16:17]
	s_mov_b32 m0, s38
	s_nop 0
	global_load_lds_dwordx4 v152, s[36:37]
	s_add_i32 m0, s38, 0x2000
	s_nop 0
	global_load_lds_dwordx4 v128, s[36:37]
	s_waitcnt vmcnt(6)
	s_waitcnt lgkmcnt(0)
	s_barrier
	s_waitcnt lgkmcnt(0)
	v_mfma_f32_16x16x32_bf16 v[60:63], v[138:141], v[186:189], v[60:63]
	v_mfma_f32_16x16x32_bf16 v[56:59], v[162:165], v[186:189], v[56:59]
	v_mfma_f32_16x16x32_bf16 v[52:55], v[138:141], v[194:197], v[52:55]
	v_mfma_f32_16x16x32_bf16 v[44:47], v[162:165], v[194:197], v[44:47]
	v_mfma_f32_16x16x32_bf16 v[36:39], v[138:141], v[202:205], v[36:39]
	v_mfma_f32_16x16x32_bf16 v[28:31], v[162:165], v[202:205], v[28:31]
	v_mfma_f32_16x16x32_bf16 v[20:23], v[138:141], v[218:221], v[20:23]
	v_mfma_f32_16x16x32_bf16 v[12:15], v[162:165], v[218:221], v[12:15]
	v_mfma_f32_16x16x32_bf16 v[60:63], v[146:149], v[190:193], v[60:63]
	v_mfma_f32_16x16x32_bf16 v[56:59], v[166:169], v[190:193], v[56:59]
	v_mfma_f32_16x16x32_bf16 v[52:55], v[146:149], v[198:201], v[52:55]
	v_mfma_f32_16x16x32_bf16 v[44:47], v[166:169], v[198:201], v[44:47]
	v_mfma_f32_16x16x32_bf16 v[36:39], v[146:149], v[214:217], v[36:39]
	v_mfma_f32_16x16x32_bf16 v[28:31], v[166:169], v[214:217], v[28:31]
	v_mfma_f32_16x16x32_bf16 v[20:23], v[146:149], v[222:225], v[20:23]
	v_mfma_f32_16x16x32_bf16 v[12:15], v[166:169], v[222:225], v[12:15]
	v_mfma_f32_16x16x32_bf16 v[48:51], v[170:173], v[186:189], v[48:51]
	v_mfma_f32_16x16x32_bf16 v[40:43], v[178:181], v[186:189], v[40:43]
	v_mfma_f32_16x16x32_bf16 v[32:35], v[170:173], v[194:197], v[32:35]
	v_mfma_f32_16x16x32_bf16 v[24:27], v[178:181], v[194:197], v[24:27]
	v_mfma_f32_16x16x32_bf16 v[16:19], v[170:173], v[202:205], v[16:19]
	v_mfma_f32_16x16x32_bf16 v[8:11], v[178:181], v[202:205], v[8:11]
	v_mfma_f32_16x16x32_bf16 v[4:7], v[170:173], v[218:221], v[4:7]
	v_mfma_f32_16x16x32_bf16 v[0:3], v[178:181], v[218:221], v[0:3]
	v_mfma_f32_16x16x32_bf16 v[48:51], v[174:177], v[190:193], v[48:51]
	v_mfma_f32_16x16x32_bf16 v[40:43], v[182:185], v[190:193], v[40:43]
	v_mfma_f32_16x16x32_bf16 v[32:35], v[174:177], v[198:201], v[32:35]
	v_mfma_f32_16x16x32_bf16 v[24:27], v[182:185], v[198:201], v[24:27]
	v_mfma_f32_16x16x32_bf16 v[16:19], v[174:177], v[214:217], v[16:19]
	v_mfma_f32_16x16x32_bf16 v[8:11], v[182:185], v[214:217], v[8:11]
	v_mfma_f32_16x16x32_bf16 v[4:7], v[174:177], v[222:225], v[4:7]
	v_mfma_f32_16x16x32_bf16 v[0:3], v[182:185], v[222:225], v[0:3]
	s_barrier
	s_mov_b32 m0, s21
	s_nop 0
	global_load_lds_dwordx4 v132, s[18:19]
	s_mov_b32 m0, s22
	s_nop 0
	global_load_lds_dwordx4 v130, s[18:19]
	s_add_i32 s36, 0, 0x18000
	s_add_i32 s37, 0, 0x1c000
	ds_read_b128 v[138:141], v236
	ds_read_b128 v[146:149], v236 offset:1024
	ds_read_b128 v[162:165], v236 offset:2048
	ds_read_b128 v[166:169], v236 offset:3072
	ds_read_b128 v[170:173], v237
	ds_read_b128 v[174:177], v237 offset:1024
	ds_read_b128 v[178:181], v237 offset:2048
	ds_read_b128 v[182:185], v237 offset:3072
	s_add_u32 s18, s18, 0x80000
	s_addc_u32 s19, s19, 0
	s_mov_b32 m0, s23
	ds_read_b128 v[186:189], v145 offset:32768
	ds_read_b128 v[190:193], v145 offset:33792
	ds_read_b128 v[194:197], v145 offset:34816
	ds_read_b128 v[198:201], v145 offset:35840
	ds_read_b128 v[202:205], v145 offset:36864
	ds_read_b128 v[214:217], v145 offset:37888
	ds_read_b128 v[218:221], v145 offset:38912
	ds_read_b128 v[222:225], v145 offset:39936
	global_load_lds_dwordx4 v132, s[18:19]
	s_mov_b32 m0, s24
	s_nop 0
	global_load_lds_dwordx4 v130, s[18:19]
	s_waitcnt vmcnt(8)
	s_waitcnt lgkmcnt(0)
	s_barrier
	s_waitcnt lgkmcnt(0)
	v_mfma_f32_16x16x32_bf16 v[124:127], v[138:141], v[186:189], v[124:127]
	v_mfma_f32_16x16x32_bf16 v[120:123], v[162:165], v[186:189], v[120:123]
	v_mfma_f32_16x16x32_bf16 v[116:119], v[138:141], v[194:197], v[116:119]
	v_mfma_f32_16x16x32_bf16 v[108:111], v[162:165], v[194:197], v[108:111]
	v_mfma_f32_16x16x32_bf16 v[100:103], v[138:141], v[202:205], v[100:103]
	v_mfma_f32_16x16x32_bf16 v[92:95], v[162:165], v[202:205], v[92:95]
	v_mfma_f32_16x16x32_bf16 v[84:87], v[138:141], v[218:221], v[84:87]
	v_mfma_f32_16x16x32_bf16 v[76:79], v[162:165], v[218:221], v[76:79]
	v_mfma_f32_16x16x32_bf16 v[124:127], v[146:149], v[190:193], v[124:127]
	v_mfma_f32_16x16x32_bf16 v[120:123], v[166:169], v[190:193], v[120:123]
	v_mfma_f32_16x16x32_bf16 v[116:119], v[146:149], v[198:201], v[116:119]
	v_mfma_f32_16x16x32_bf16 v[108:111], v[166:169], v[198:201], v[108:111]
	v_mfma_f32_16x16x32_bf16 v[100:103], v[146:149], v[214:217], v[100:103]
	v_mfma_f32_16x16x32_bf16 v[92:95], v[166:169], v[214:217], v[92:95]
	v_mfma_f32_16x16x32_bf16 v[84:87], v[146:149], v[222:225], v[84:87]
	v_mfma_f32_16x16x32_bf16 v[76:79], v[166:169], v[222:225], v[76:79]
	v_mfma_f32_16x16x32_bf16 v[112:115], v[170:173], v[186:189], v[112:115]
	v_mfma_f32_16x16x32_bf16 v[104:107], v[178:181], v[186:189], v[104:107]
	v_mfma_f32_16x16x32_bf16 v[96:99], v[170:173], v[194:197], v[96:99]
	v_mfma_f32_16x16x32_bf16 v[88:91], v[178:181], v[194:197], v[88:91]
	v_mfma_f32_16x16x32_bf16 v[80:83], v[170:173], v[202:205], v[80:83]
	v_mfma_f32_16x16x32_bf16 v[72:75], v[178:181], v[202:205], v[72:75]
	v_mfma_f32_16x16x32_bf16 v[68:71], v[170:173], v[218:221], v[68:71]
	v_mfma_f32_16x16x32_bf16 v[64:67], v[178:181], v[218:221], v[64:67]
	v_mfma_f32_16x16x32_bf16 v[112:115], v[174:177], v[190:193], v[112:115]
	v_mfma_f32_16x16x32_bf16 v[104:107], v[182:185], v[190:193], v[104:107]
	v_mfma_f32_16x16x32_bf16 v[96:99], v[174:177], v[198:201], v[96:99]
	v_mfma_f32_16x16x32_bf16 v[88:91], v[182:185], v[198:201], v[88:91]
	v_mfma_f32_16x16x32_bf16 v[80:83], v[174:177], v[214:217], v[80:83]
	v_mfma_f32_16x16x32_bf16 v[72:75], v[182:185], v[214:217], v[72:75]
	v_mfma_f32_16x16x32_bf16 v[68:71], v[174:177], v[222:225], v[68:71]
	v_mfma_f32_16x16x32_bf16 v[64:67], v[182:185], v[222:225], v[64:67]
	s_barrier
	s_add_i32 s18, s36, s20
	s_mov_b32 m0, s18
	ds_read_b128 v[186:189], v145 offset:49152
	ds_read_b128 v[190:193], v145 offset:50176
	ds_read_b128 v[194:197], v145 offset:51200
	ds_read_b128 v[198:201], v145 offset:52224
	ds_read_b128 v[202:205], v145 offset:53248
	ds_read_b128 v[214:217], v145 offset:54272
	ds_read_b128 v[218:221], v145 offset:55296
	ds_read_b128 v[222:225], v145 offset:56320
	global_load_lds_dwordx4 v152, s[100:101]
	s_add_i32 m0, s18, 0x2000
	s_add_u32 s16, s16, 0x80080
	s_addc_u32 s17, s17, 0
	s_add_i32 s18, s37, s20
	global_load_lds_dwordx4 v128, s[100:101]
	s_mov_b32 m0, s18
	s_nop 0
	global_load_lds_dwordx4 v152, s[16:17]
	s_add_i32 m0, s18, 0x2000
	s_nop 0
	global_load_lds_dwordx4 v128, s[16:17]
	s_waitcnt vmcnt(6)
	s_waitcnt lgkmcnt(0)
	s_barrier
	s_waitcnt lgkmcnt(0)
	v_mfma_f32_16x16x32_bf16 v[60:63], v[138:141], v[186:189], v[60:63]
	v_mfma_f32_16x16x32_bf16 v[56:59], v[162:165], v[186:189], v[56:59]
	v_mfma_f32_16x16x32_bf16 v[52:55], v[138:141], v[194:197], v[52:55]
	v_mfma_f32_16x16x32_bf16 v[44:47], v[162:165], v[194:197], v[44:47]
	v_mfma_f32_16x16x32_bf16 v[36:39], v[138:141], v[202:205], v[36:39]
	v_mfma_f32_16x16x32_bf16 v[28:31], v[162:165], v[202:205], v[28:31]
	v_mfma_f32_16x16x32_bf16 v[20:23], v[138:141], v[218:221], v[20:23]
	v_mfma_f32_16x16x32_bf16 v[12:15], v[162:165], v[218:221], v[12:15]
	v_mfma_f32_16x16x32_bf16 v[60:63], v[146:149], v[190:193], v[60:63]
	v_mfma_f32_16x16x32_bf16 v[56:59], v[166:169], v[190:193], v[56:59]
	v_mfma_f32_16x16x32_bf16 v[52:55], v[146:149], v[198:201], v[52:55]
	v_mfma_f32_16x16x32_bf16 v[44:47], v[166:169], v[198:201], v[44:47]
	v_mfma_f32_16x16x32_bf16 v[36:39], v[146:149], v[214:217], v[36:39]
	v_mfma_f32_16x16x32_bf16 v[28:31], v[166:169], v[214:217], v[28:31]
	v_mfma_f32_16x16x32_bf16 v[20:23], v[146:149], v[222:225], v[20:23]
	v_mfma_f32_16x16x32_bf16 v[12:15], v[166:169], v[222:225], v[12:15]
	v_mfma_f32_16x16x32_bf16 v[48:51], v[170:173], v[186:189], v[48:51]
	v_mfma_f32_16x16x32_bf16 v[40:43], v[178:181], v[186:189], v[40:43]
	v_mfma_f32_16x16x32_bf16 v[32:35], v[170:173], v[194:197], v[32:35]
	v_mfma_f32_16x16x32_bf16 v[24:27], v[178:181], v[194:197], v[24:27]
	v_mfma_f32_16x16x32_bf16 v[16:19], v[170:173], v[202:205], v[16:19]
	v_mfma_f32_16x16x32_bf16 v[8:11], v[178:181], v[202:205], v[8:11]
	v_mfma_f32_16x16x32_bf16 v[4:7], v[170:173], v[218:221], v[4:7]
	v_mfma_f32_16x16x32_bf16 v[0:3], v[178:181], v[218:221], v[0:3]
	v_mfma_f32_16x16x32_bf16 v[48:51], v[174:177], v[190:193], v[48:51]
	v_mfma_f32_16x16x32_bf16 v[40:43], v[182:185], v[190:193], v[40:43]
	v_mfma_f32_16x16x32_bf16 v[32:35], v[174:177], v[198:201], v[32:35]
	v_mfma_f32_16x16x32_bf16 v[24:27], v[182:185], v[198:201], v[24:27]
	v_mfma_f32_16x16x32_bf16 v[16:19], v[174:177], v[214:217], v[16:19]
	v_mfma_f32_16x16x32_bf16 v[8:11], v[182:185], v[214:217], v[8:11]
	v_mfma_f32_16x16x32_bf16 v[4:7], v[174:177], v[222:225], v[4:7]
	v_mfma_f32_16x16x32_bf16 v[0:3], v[182:185], v[222:225], v[0:3]
	s_barrier
	s_add_i32 s35, s35, 2
	s_add_u32 s33, s33, 0x100
	s_addc_u32 s34, s34, 0
	s_add_u32 s14, s14, 0x100
	s_addc_u32 s15, s15, 0
	s_cmp_gt_u32 s35, 29
	s_cbranch_scc0 .LBB0_192
	s_setprio 0
	s_and_b64 vcc, exec, s[4:5]
	s_cbranch_vccz .LBB0_195
	s_barrier

.LBB0_1382:
	s_ashr_i32 s9, s8, 31
	s_lshl_b64 s[10:11], s[8:9], 20
	s_add_u32 s10, s66, s10
	s_addc_u32 s11, s67, s11
	s_and_b64 s[12:13], s[0:1], exec
	s_cselect_b32 s9, s11, s15
	s_cselect_b32 s33, s10, s14
	s_ashr_i32 s7, s6, 31
	s_lshl_b64 s[12:13], s[6:7], 20
	s_add_u32 s12, s60, s12
	s_addc_u32 s13, s61, s13
	s_and_b64 s[18:19], s[0:1], exec
	s_cselect_b32 s7, s13, s17
	s_cselect_b32 s34, s12, s16
	s_add_u32 s35, s16, 0x100
	v_mov_b32_e32 v0, 0
	s_addc_u32 s36, s17, 0
	s_mov_b32 s37, -2
	v_mov_b32_e32 v1, v0
	v_mov_b32_e32 v2, v0
	v_mov_b32_e32 v3, v0
	v_mov_b32_e32 v4, v0
	v_mov_b32_e32 v5, v0
	v_mov_b32_e32 v6, v0
	v_mov_b32_e32 v7, v0
	v_mov_b32_e32 v16, v0
	v_mov_b32_e32 v17, v0
	v_mov_b32_e32 v18, v0
	v_mov_b32_e32 v19, v0
	v_mov_b32_e32 v20, v0
	v_mov_b32_e32 v21, v0
	v_mov_b32_e32 v22, v0
	v_mov_b32_e32 v23, v0
	v_mov_b32_e32 v32, v0
	v_mov_b32_e32 v33, v0
	v_mov_b32_e32 v34, v0
	v_mov_b32_e32 v35, v0
	v_mov_b32_e32 v36, v0
	v_mov_b32_e32 v37, v0
	v_mov_b32_e32 v38, v0
	v_mov_b32_e32 v39, v0
	v_mov_b32_e32 v48, v0
	v_mov_b32_e32 v49, v0
	v_mov_b32_e32 v50, v0
	v_mov_b32_e32 v51, v0
	v_mov_b32_e32 v52, v0
	v_mov_b32_e32 v53, v0
	v_mov_b32_e32 v54, v0
	v_mov_b32_e32 v55, v0
	v_mov_b32_e32 v8, v0
	v_mov_b32_e32 v9, v0
	v_mov_b32_e32 v10, v0
	v_mov_b32_e32 v11, v0
	v_mov_b32_e32 v12, v0
	v_mov_b32_e32 v13, v0
	v_mov_b32_e32 v14, v0
	v_mov_b32_e32 v15, v0
	v_mov_b32_e32 v24, v0
	v_mov_b32_e32 v25, v0
	v_mov_b32_e32 v26, v0
	v_mov_b32_e32 v27, v0
	v_mov_b32_e32 v28, v0
	v_mov_b32_e32 v29, v0
	v_mov_b32_e32 v30, v0
	v_mov_b32_e32 v31, v0
	v_mov_b32_e32 v40, v0
	v_mov_b32_e32 v41, v0
	v_mov_b32_e32 v42, v0
	v_mov_b32_e32 v43, v0
	v_mov_b32_e32 v44, v0
	v_mov_b32_e32 v45, v0
	v_mov_b32_e32 v46, v0
	v_mov_b32_e32 v47, v0
	v_mov_b32_e32 v56, v0
	v_mov_b32_e32 v57, v0
	v_mov_b32_e32 v58, v0
	v_mov_b32_e32 v59, v0
	v_mov_b32_e32 v60, v0
	v_mov_b32_e32 v61, v0
	v_mov_b32_e32 v62, v0
	v_mov_b32_e32 v63, v0
	v_mov_b32_e32 v64, v0
	v_mov_b32_e32 v65, v0
	v_mov_b32_e32 v66, v0
	v_mov_b32_e32 v67, v0
	v_mov_b32_e32 v68, v0
	v_mov_b32_e32 v69, v0
	v_mov_b32_e32 v70, v0
	v_mov_b32_e32 v71, v0
	v_mov_b32_e32 v80, v0
	v_mov_b32_e32 v81, v0
	v_mov_b32_e32 v82, v0
	v_mov_b32_e32 v83, v0
	v_mov_b32_e32 v84, v0
	v_mov_b32_e32 v85, v0
	v_mov_b32_e32 v86, v0
	v_mov_b32_e32 v87, v0
	v_mov_b32_e32 v96, v0
	v_mov_b32_e32 v97, v0
	v_mov_b32_e32 v98, v0
	v_mov_b32_e32 v99, v0
	v_mov_b32_e32 v100, v0
	v_mov_b32_e32 v101, v0
	v_mov_b32_e32 v102, v0
	v_mov_b32_e32 v103, v0
	v_mov_b32_e32 v112, v0
	v_mov_b32_e32 v113, v0
	v_mov_b32_e32 v114, v0
	v_mov_b32_e32 v115, v0
	v_mov_b32_e32 v116, v0
	v_mov_b32_e32 v117, v0
	v_mov_b32_e32 v118, v0
	v_mov_b32_e32 v119, v0
	v_mov_b32_e32 v72, v0
	v_mov_b32_e32 v73, v0
	v_mov_b32_e32 v74, v0
	v_mov_b32_e32 v75, v0
	v_mov_b32_e32 v76, v0
	v_mov_b32_e32 v77, v0
	v_mov_b32_e32 v78, v0
	v_mov_b32_e32 v79, v0
	v_mov_b32_e32 v88, v0
	v_mov_b32_e32 v89, v0
	v_mov_b32_e32 v90, v0
	v_mov_b32_e32 v91, v0
	v_mov_b32_e32 v92, v0
	v_mov_b32_e32 v93, v0
	v_mov_b32_e32 v94, v0
	v_mov_b32_e32 v95, v0
	v_mov_b32_e32 v104, v0
	v_mov_b32_e32 v105, v0
	v_mov_b32_e32 v106, v0
	v_mov_b32_e32 v107, v0
	v_mov_b32_e32 v108, v0
	v_mov_b32_e32 v109, v0
	v_mov_b32_e32 v110, v0
	v_mov_b32_e32 v111, v0
	v_mov_b32_e32 v120, v0
	v_mov_b32_e32 v121, v0
	v_mov_b32_e32 v122, v0
	v_mov_b32_e32 v123, v0
	v_mov_b32_e32 v124, v0
	v_mov_b32_e32 v125, v0
	v_mov_b32_e32 v126, v0
	v_mov_b32_e32 v127, v0
	s_mov_b64 s[74:75], 0x80
	s_waitcnt vmcnt(0)
	v_add_u32_e32 v234, 0x10000, v141
	v_add_u32_e32 v235, 0x14000, v141
	v_add_u32_e32 v236, 0x18000, v141
	v_add_u32_e32 v237, 0x1c000, v141
	s_cmpk_ge_u32 s47, 0x100
	s_cbranch_scc0 .Lmy_pr_1
	s_setprio 1
.Lmy_pr_1:
.LBB0_1383:
	s_add_u32 s98, s14, 0xfff80000
	s_addc_u32 s99, s15, -1
	s_mov_b32 m0, s27
	s_nop 0
	global_load_lds_dwordx4 v132, s[98:99]
	s_mov_b32 m0, s28
	s_nop 0
	global_load_lds_dwordx4 v130, s[98:99]
	s_add_u32 s16, s14, 0x100
	s_addc_u32 s17, s15, 0
	s_add_i32 s40, 0, 0x10000
	s_cmp_eq_u32 s37, 28
	s_cselect_b32 s21, s9, s17
	s_cselect_b32 s20, s33, s16
	s_cselect_b32 s19, s7, s36
	s_cselect_b32 s18, s34, s35
	s_add_i32 s41, 0, 0x14000
	ds_read_b128 v[134:137], v234
	ds_read_b128 v[144:147], v234 offset:1024
	ds_read_b128 v[148:151], v234 offset:2048
	ds_read_b128 v[162:165], v234 offset:3072
	ds_read_b128 v[166:169], v235
	ds_read_b128 v[170:173], v235 offset:1024
	ds_read_b128 v[174:177], v235 offset:2048
	ds_read_b128 v[178:181], v235 offset:3072
	s_add_i32 m0, s23, 0xc000
	ds_read_b128 v[182:185], v143
	ds_read_b128 v[186:189], v143 offset:1024
	ds_read_b128 v[190:193], v143 offset:2048
	ds_read_b128 v[194:197], v143 offset:3072
	ds_read_b128 v[198:201], v143 offset:4096
	ds_read_b128 v[202:205], v143 offset:5120
	ds_read_b128 v[214:217], v143 offset:6144
	ds_read_b128 v[218:221], v143 offset:7168
	global_load_lds_dwordx4 v132, s[14:15]
	s_add_i32 m0, s23, 0xe000
	s_nop 0
	global_load_lds_dwordx4 v130, s[14:15]
	s_waitcnt vmcnt(8)
	s_waitcnt lgkmcnt(0)
	s_barrier
	s_waitcnt lgkmcnt(0)
	v_mfma_f32_16x16x32_bf16 v[124:127], v[134:137], v[182:185], v[124:127]
	v_mfma_f32_16x16x32_bf16 v[120:123], v[148:151], v[182:185], v[120:123]
	v_mfma_f32_16x16x32_bf16 v[108:111], v[134:137], v[190:193], v[108:111]
	v_mfma_f32_16x16x32_bf16 v[104:107], v[148:151], v[190:193], v[104:107]
	v_mfma_f32_16x16x32_bf16 v[92:95], v[134:137], v[198:201], v[92:95]
	v_mfma_f32_16x16x32_bf16 v[88:91], v[148:151], v[198:201], v[88:91]
	v_mfma_f32_16x16x32_bf16 v[76:79], v[134:137], v[214:217], v[76:79]
	v_mfma_f32_16x16x32_bf16 v[72:75], v[148:151], v[214:217], v[72:75]
	v_mfma_f32_16x16x32_bf16 v[124:127], v[144:147], v[186:189], v[124:127]
	v_mfma_f32_16x16x32_bf16 v[120:123], v[162:165], v[186:189], v[120:123]
	v_mfma_f32_16x16x32_bf16 v[108:111], v[144:147], v[194:197], v[108:111]
	v_mfma_f32_16x16x32_bf16 v[104:107], v[162:165], v[194:197], v[104:107]
	v_mfma_f32_16x16x32_bf16 v[92:95], v[144:147], v[202:205], v[92:95]
	v_mfma_f32_16x16x32_bf16 v[88:91], v[162:165], v[202:205], v[88:91]
	v_mfma_f32_16x16x32_bf16 v[76:79], v[144:147], v[218:221], v[76:79]
	v_mfma_f32_16x16x32_bf16 v[72:75], v[162:165], v[218:221], v[72:75]
	v_mfma_f32_16x16x32_bf16 v[116:119], v[166:169], v[182:185], v[116:119]
	v_mfma_f32_16x16x32_bf16 v[112:115], v[174:177], v[182:185], v[112:115]
	v_mfma_f32_16x16x32_bf16 v[100:103], v[166:169], v[190:193], v[100:103]
	v_mfma_f32_16x16x32_bf16 v[96:99], v[174:177], v[190:193], v[96:99]
	v_mfma_f32_16x16x32_bf16 v[84:87], v[166:169], v[198:201], v[84:87]
	v_mfma_f32_16x16x32_bf16 v[80:83], v[174:177], v[198:201], v[80:83]
	v_mfma_f32_16x16x32_bf16 v[68:71], v[166:169], v[214:217], v[68:71]
	v_mfma_f32_16x16x32_bf16 v[64:67], v[174:177], v[214:217], v[64:67]
	v_mfma_f32_16x16x32_bf16 v[116:119], v[170:173], v[186:189], v[116:119]
	v_mfma_f32_16x16x32_bf16 v[112:115], v[178:181], v[186:189], v[112:115]
	v_mfma_f32_16x16x32_bf16 v[100:103], v[170:173], v[194:197], v[100:103]
	v_mfma_f32_16x16x32_bf16 v[96:99], v[178:181], v[194:197], v[96:99]
	v_mfma_f32_16x16x32_bf16 v[84:87], v[170:173], v[202:205], v[84:87]
	v_mfma_f32_16x16x32_bf16 v[80:83], v[178:181], v[202:205], v[80:83]
	v_mfma_f32_16x16x32_bf16 v[68:71], v[170:173], v[218:221], v[68:71]
	v_mfma_f32_16x16x32_bf16 v[64:67], v[178:181], v[218:221], v[64:67]
	s_barrier
	s_add_i32 s14, s40, s22
	s_add_u32 s100, s18, 0x80
	s_addc_u32 s101, s19, 0
	s_mov_b32 m0, s14
	ds_read_b128 v[182:185], v143 offset:16384
	ds_read_b128 v[186:189], v143 offset:17408
	ds_read_b128 v[190:193], v143 offset:18432
	ds_read_b128 v[194:197], v143 offset:19456
	ds_read_b128 v[198:201], v143 offset:20480
	ds_read_b128 v[202:205], v143 offset:21504
	ds_read_b128 v[214:217], v143 offset:22528
	ds_read_b128 v[218:221], v143 offset:23552
	global_load_lds_dwordx4 v152, s[18:19]
	s_add_i32 m0, s14, 0x2000
	s_add_u32 s14, s18, 0x80000
	s_addc_u32 s15, s19, 0
	s_add_i32 s40, s41, s22
	global_load_lds_dwordx4 v128, s[18:19]
	s_mov_b32 m0, s40
	s_nop 0
	global_load_lds_dwordx4 v152, s[14:15]
	s_add_i32 m0, s40, 0x2000
	s_nop 0
	global_load_lds_dwordx4 v128, s[14:15]
	s_waitcnt vmcnt(6)
	s_waitcnt lgkmcnt(0)
	s_barrier
	s_waitcnt lgkmcnt(0)
	v_mfma_f32_16x16x32_bf16 v[60:63], v[134:137], v[182:185], v[60:63]
	v_mfma_f32_16x16x32_bf16 v[56:59], v[148:151], v[182:185], v[56:59]
	v_mfma_f32_16x16x32_bf16 v[44:47], v[134:137], v[190:193], v[44:47]
	v_mfma_f32_16x16x32_bf16 v[40:43], v[148:151], v[190:193], v[40:43]
	v_mfma_f32_16x16x32_bf16 v[28:31], v[134:137], v[198:201], v[28:31]
	v_mfma_f32_16x16x32_bf16 v[24:27], v[148:151], v[198:201], v[24:27]
	v_mfma_f32_16x16x32_bf16 v[12:15], v[134:137], v[214:217], v[12:15]
	v_mfma_f32_16x16x32_bf16 v[8:11], v[148:151], v[214:217], v[8:11]
	v_mfma_f32_16x16x32_bf16 v[60:63], v[144:147], v[186:189], v[60:63]
	v_mfma_f32_16x16x32_bf16 v[56:59], v[162:165], v[186:189], v[56:59]
	v_mfma_f32_16x16x32_bf16 v[44:47], v[144:147], v[194:197], v[44:47]
	v_mfma_f32_16x16x32_bf16 v[40:43], v[162:165], v[194:197], v[40:43]
	v_mfma_f32_16x16x32_bf16 v[28:31], v[144:147], v[202:205], v[28:31]
	v_mfma_f32_16x16x32_bf16 v[24:27], v[162:165], v[202:205], v[24:27]
	v_mfma_f32_16x16x32_bf16 v[12:15], v[144:147], v[218:221], v[12:15]
	v_mfma_f32_16x16x32_bf16 v[8:11], v[162:165], v[218:221], v[8:11]
	v_mfma_f32_16x16x32_bf16 v[52:55], v[166:169], v[182:185], v[52:55]
	v_mfma_f32_16x16x32_bf16 v[48:51], v[174:177], v[182:185], v[48:51]
	v_mfma_f32_16x16x32_bf16 v[36:39], v[166:169], v[190:193], v[36:39]
	v_mfma_f32_16x16x32_bf16 v[32:35], v[174:177], v[190:193], v[32:35]
	v_mfma_f32_16x16x32_bf16 v[20:23], v[166:169], v[198:201], v[20:23]
	v_mfma_f32_16x16x32_bf16 v[16:19], v[174:177], v[198:201], v[16:19]
	v_mfma_f32_16x16x32_bf16 v[4:7], v[166:169], v[214:217], v[4:7]
	v_mfma_f32_16x16x32_bf16 v[0:3], v[174:177], v[214:217], v[0:3]
	v_mfma_f32_16x16x32_bf16 v[52:55], v[170:173], v[186:189], v[52:55]
	v_mfma_f32_16x16x32_bf16 v[48:51], v[178:181], v[186:189], v[48:51]
	v_mfma_f32_16x16x32_bf16 v[36:39], v[170:173], v[194:197], v[36:39]
	v_mfma_f32_16x16x32_bf16 v[32:35], v[178:181], v[194:197], v[32:35]
	v_mfma_f32_16x16x32_bf16 v[20:23], v[170:173], v[202:205], v[20:23]
	v_mfma_f32_16x16x32_bf16 v[16:19], v[178:181], v[202:205], v[16:19]
	v_mfma_f32_16x16x32_bf16 v[4:7], v[170:173], v[218:221], v[4:7]
	v_mfma_f32_16x16x32_bf16 v[0:3], v[178:181], v[218:221], v[0:3]
	s_barrier
	s_mov_b32 m0, s23
	s_nop 0
	global_load_lds_dwordx4 v152, s[20:21]
	s_mov_b32 m0, s24
	s_nop 0
	global_load_lds_dwordx4 v128, s[20:21]
	s_add_i32 s40, 0, 0x18000
	s_add_i32 s41, 0, 0x1c000
	ds_read_b128 v[134:137], v236
	ds_read_b128 v[144:147], v236 offset:1024
	ds_read_b128 v[148:151], v236 offset:2048
	ds_read_b128 v[162:165], v236 offset:3072
	ds_read_b128 v[166:169], v237
	ds_read_b128 v[170:173], v237 offset:1024
	ds_read_b128 v[174:177], v237 offset:2048
	ds_read_b128 v[178:181], v237 offset:3072
	s_add_u32 s14, s20, 0x80000
	s_addc_u32 s15, s21, 0
	s_mov_b32 m0, s25
	ds_read_b128 v[182:185], v143 offset:32768
	ds_read_b128 v[186:189], v143 offset:33792
	ds_read_b128 v[190:193], v143 offset:34816
	ds_read_b128 v[194:197], v143 offset:35840
	ds_read_b128 v[198:201], v143 offset:36864
	ds_read_b128 v[202:205], v143 offset:37888
	ds_read_b128 v[214:217], v143 offset:38912
	ds_read_b128 v[218:221], v143 offset:39936
	global_load_lds_dwordx4 v152, s[14:15]
	s_mov_b32 m0, s26
	s_nop 0
	global_load_lds_dwordx4 v128, s[14:15]
	s_waitcnt vmcnt(8)
	s_waitcnt lgkmcnt(0)
	s_barrier
	s_waitcnt lgkmcnt(0)
	v_mfma_f32_16x16x32_bf16 v[124:127], v[134:137], v[182:185], v[124:127]
	v_mfma_f32_16x16x32_bf16 v[120:123], v[148:151], v[182:185], v[120:123]
	v_mfma_f32_16x16x32_bf16 v[108:111], v[134:137], v[190:193], v[108:111]
	v_mfma_f32_16x16x32_bf16 v[104:107], v[148:151], v[190:193], v[104:107]
	v_mfma_f32_16x16x32_bf16 v[92:95], v[134:137], v[198:201], v[92:95]
	v_mfma_f32_16x16x32_bf16 v[88:91], v[148:151], v[198:201], v[88:91]
	v_mfma_f32_16x16x32_bf16 v[76:79], v[134:137], v[214:217], v[76:79]
	v_mfma_f32_16x16x32_bf16 v[72:75], v[148:151], v[214:217], v[72:75]
	v_mfma_f32_16x16x32_bf16 v[124:127], v[144:147], v[186:189], v[124:127]
	v_mfma_f32_16x16x32_bf16 v[120:123], v[162:165], v[186:189], v[120:123]
	v_mfma_f32_16x16x32_bf16 v[108:111], v[144:147], v[194:197], v[108:111]
	v_mfma_f32_16x16x32_bf16 v[104:107], v[162:165], v[194:197], v[104:107]
	v_mfma_f32_16x16x32_bf16 v[92:95], v[144:147], v[202:205], v[92:95]
	v_mfma_f32_16x16x32_bf16 v[88:91], v[162:165], v[202:205], v[88:91]
	v_mfma_f32_16x16x32_bf16 v[76:79], v[144:147], v[218:221], v[76:79]
	v_mfma_f32_16x16x32_bf16 v[72:75], v[162:165], v[218:221], v[72:75]
	v_mfma_f32_16x16x32_bf16 v[116:119], v[166:169], v[182:185], v[116:119]
	v_mfma_f32_16x16x32_bf16 v[112:115], v[174:177], v[182:185], v[112:115]
	v_mfma_f32_16x16x32_bf16 v[100:103], v[166:169], v[190:193], v[100:103]
	v_mfma_f32_16x16x32_bf16 v[96:99], v[174:177], v[190:193], v[96:99]
	v_mfma_f32_16x16x32_bf16 v[84:87], v[166:169], v[198:201], v[84:87]
	v_mfma_f32_16x16x32_bf16 v[80:83], v[174:177], v[198:201], v[80:83]
	v_mfma_f32_16x16x32_bf16 v[68:71], v[166:169], v[214:217], v[68:71]
	v_mfma_f32_16x16x32_bf16 v[64:67], v[174:177], v[214:217], v[64:67]
	v_mfma_f32_16x16x32_bf16 v[116:119], v[170:173], v[186:189], v[116:119]
	v_mfma_f32_16x16x32_bf16 v[112:115], v[178:181], v[186:189], v[112:115]
	v_mfma_f32_16x16x32_bf16 v[100:103], v[170:173], v[194:197], v[100:103]
	v_mfma_f32_16x16x32_bf16 v[96:99], v[178:181], v[194:197], v[96:99]
	v_mfma_f32_16x16x32_bf16 v[84:87], v[170:173], v[202:205], v[84:87]
	v_mfma_f32_16x16x32_bf16 v[80:83], v[178:181], v[202:205], v[80:83]
	v_mfma_f32_16x16x32_bf16 v[68:71], v[170:173], v[218:221], v[68:71]
	v_mfma_f32_16x16x32_bf16 v[64:67], v[178:181], v[218:221], v[64:67]
	s_barrier
	s_add_i32 s14, s40, s22
	s_mov_b32 m0, s14
	ds_read_b128 v[182:185], v143 offset:49152
	ds_read_b128 v[186:189], v143 offset:50176
	ds_read_b128 v[190:193], v143 offset:51200
	ds_read_b128 v[194:197], v143 offset:52224
	ds_read_b128 v[198:201], v143 offset:53248
	ds_read_b128 v[202:205], v143 offset:54272
	ds_read_b128 v[214:217], v143 offset:55296
	ds_read_b128 v[218:221], v143 offset:56320
	global_load_lds_dwordx4 v152, s[100:101]
	s_add_i32 m0, s14, 0x2000
	s_add_u32 s14, s18, 0x80080
	s_addc_u32 s15, s19, 0
	s_add_i32 s18, s41, s22
	global_load_lds_dwordx4 v128, s[100:101]
	s_mov_b32 m0, s18
	s_nop 0
	global_load_lds_dwordx4 v152, s[14:15]
	s_add_i32 m0, s18, 0x2000
	s_nop 0
	global_load_lds_dwordx4 v128, s[14:15]
	s_waitcnt vmcnt(6)
	s_waitcnt lgkmcnt(0)
	s_barrier
	s_waitcnt lgkmcnt(0)
	v_mfma_f32_16x16x32_bf16 v[60:63], v[134:137], v[182:185], v[60:63]
	v_mfma_f32_16x16x32_bf16 v[56:59], v[148:151], v[182:185], v[56:59]
	v_mfma_f32_16x16x32_bf16 v[44:47], v[134:137], v[190:193], v[44:47]
	v_mfma_f32_16x16x32_bf16 v[40:43], v[148:151], v[190:193], v[40:43]
	v_mfma_f32_16x16x32_bf16 v[28:31], v[134:137], v[198:201], v[28:31]
	v_mfma_f32_16x16x32_bf16 v[24:27], v[148:151], v[198:201], v[24:27]
	v_mfma_f32_16x16x32_bf16 v[12:15], v[134:137], v[214:217], v[12:15]
	v_mfma_f32_16x16x32_bf16 v[8:11], v[148:151], v[214:217], v[8:11]
	v_mfma_f32_16x16x32_bf16 v[60:63], v[144:147], v[186:189], v[60:63]
	v_mfma_f32_16x16x32_bf16 v[56:59], v[162:165], v[186:189], v[56:59]
	v_mfma_f32_16x16x32_bf16 v[44:47], v[144:147], v[194:197], v[44:47]
	v_mfma_f32_16x16x32_bf16 v[40:43], v[162:165], v[194:197], v[40:43]
	v_mfma_f32_16x16x32_bf16 v[28:31], v[144:147], v[202:205], v[28:31]
	v_mfma_f32_16x16x32_bf16 v[24:27], v[162:165], v[202:205], v[24:27]
	v_mfma_f32_16x16x32_bf16 v[12:15], v[144:147], v[218:221], v[12:15]
	v_mfma_f32_16x16x32_bf16 v[8:11], v[162:165], v[218:221], v[8:11]
	v_mfma_f32_16x16x32_bf16 v[52:55], v[166:169], v[182:185], v[52:55]
	v_mfma_f32_16x16x32_bf16 v[48:51], v[174:177], v[182:185], v[48:51]
	v_mfma_f32_16x16x32_bf16 v[36:39], v[166:169], v[190:193], v[36:39]
	v_mfma_f32_16x16x32_bf16 v[32:35], v[174:177], v[190:193], v[32:35]
	v_mfma_f32_16x16x32_bf16 v[20:23], v[166:169], v[198:201], v[20:23]
	v_mfma_f32_16x16x32_bf16 v[16:19], v[174:177], v[198:201], v[16:19]
	v_mfma_f32_16x16x32_bf16 v[4:7], v[166:169], v[214:217], v[4:7]
	v_mfma_f32_16x16x32_bf16 v[0:3], v[174:177], v[214:217], v[0:3]
	v_mfma_f32_16x16x32_bf16 v[52:55], v[170:173], v[186:189], v[52:55]
	v_mfma_f32_16x16x32_bf16 v[48:51], v[178:181], v[186:189], v[48:51]
	v_mfma_f32_16x16x32_bf16 v[36:39], v[170:173], v[194:197], v[36:39]
	v_mfma_f32_16x16x32_bf16 v[32:35], v[178:181], v[194:197], v[32:35]
	v_mfma_f32_16x16x32_bf16 v[20:23], v[170:173], v[202:205], v[20:23]
	v_mfma_f32_16x16x32_bf16 v[16:19], v[178:181], v[202:205], v[16:19]
	v_mfma_f32_16x16x32_bf16 v[4:7], v[170:173], v[218:221], v[4:7]
	v_mfma_f32_16x16x32_bf16 v[0:3], v[178:181], v[218:221], v[0:3]
	s_barrier
	s_add_i32 s37, s37, 2
	s_add_u32 s35, s35, 0x100
	s_addc_u32 s36, s36, 0
	s_cmp_gt_u32 s37, 29
	s_mov_b64 s[14:15], s[16:17]
	s_cbranch_scc0 .LBB0_1383
	s_setprio 0
	s_and_b64 vcc, exec, s[4:5]
	s_cbranch_vccz .LBB0_1386
	s_barrier

.LBB0_1509:
	s_ashr_i32 s9, s8, 31
	s_lshl_b64 s[10:11], s[8:9], 20
	s_add_u32 s10, s66, s10
	s_addc_u32 s11, s67, s11
	s_and_b64 s[12:13], s[0:1], exec
	s_cselect_b32 s9, s11, s15
	s_cselect_b32 s30, s10, s14
	s_ashr_i32 s7, s6, 31
	s_lshl_b64 s[12:13], s[6:7], 20
	s_add_u32 s12, s62, s12
	s_addc_u32 s13, s63, s13
	s_and_b64 s[18:19], s[0:1], exec
	s_cselect_b32 s7, s13, s17
	s_cselect_b32 s31, s12, s16
	s_add_u32 s33, s16, 0x100
	s_addc_u32 s34, s17, 0
	s_add_u32 s14, s14, 0x80080
	v_mov_b32_e32 v0, 0
	s_addc_u32 s15, s15, 0
	s_mov_b32 s35, -2
	v_mov_b32_e32 v1, v0
	v_mov_b32_e32 v2, v0
	v_mov_b32_e32 v3, v0
	v_mov_b32_e32 v8, v0
	v_mov_b32_e32 v9, v0
	v_mov_b32_e32 v10, v0
	v_mov_b32_e32 v11, v0
	v_mov_b32_e32 v16, v0
	v_mov_b32_e32 v17, v0
	v_mov_b32_e32 v18, v0
	v_mov_b32_e32 v19, v0
	v_mov_b32_e32 v24, v0
	v_mov_b32_e32 v25, v0
	v_mov_b32_e32 v26, v0
	v_mov_b32_e32 v27, v0
	v_mov_b32_e32 v32, v0
	v_mov_b32_e32 v33, v0
	v_mov_b32_e32 v34, v0
	v_mov_b32_e32 v35, v0
	v_mov_b32_e32 v40, v0
	v_mov_b32_e32 v41, v0
	v_mov_b32_e32 v42, v0
	v_mov_b32_e32 v43, v0
	v_mov_b32_e32 v48, v0
	v_mov_b32_e32 v49, v0
	v_mov_b32_e32 v50, v0
	v_mov_b32_e32 v51, v0
	v_mov_b32_e32 v56, v0
	v_mov_b32_e32 v57, v0
	v_mov_b32_e32 v58, v0
	v_mov_b32_e32 v59, v0
	v_mov_b32_e32 v4, v0
	v_mov_b32_e32 v5, v0
	v_mov_b32_e32 v6, v0
	v_mov_b32_e32 v7, v0
	v_mov_b32_e32 v12, v0
	v_mov_b32_e32 v13, v0
	v_mov_b32_e32 v14, v0
	v_mov_b32_e32 v15, v0
	v_mov_b32_e32 v20, v0
	v_mov_b32_e32 v21, v0
	v_mov_b32_e32 v22, v0
	v_mov_b32_e32 v23, v0
	v_mov_b32_e32 v28, v0
	v_mov_b32_e32 v29, v0
	v_mov_b32_e32 v30, v0
	v_mov_b32_e32 v31, v0
	v_mov_b32_e32 v36, v0
	v_mov_b32_e32 v37, v0
	v_mov_b32_e32 v38, v0
	v_mov_b32_e32 v39, v0
	v_mov_b32_e32 v44, v0
	v_mov_b32_e32 v45, v0
	v_mov_b32_e32 v46, v0
	v_mov_b32_e32 v47, v0
	v_mov_b32_e32 v52, v0
	v_mov_b32_e32 v53, v0
	v_mov_b32_e32 v54, v0
	v_mov_b32_e32 v55, v0
	v_mov_b32_e32 v60, v0
	v_mov_b32_e32 v61, v0
	v_mov_b32_e32 v62, v0
	v_mov_b32_e32 v63, v0
	v_mov_b32_e32 v64, v0
	v_mov_b32_e32 v65, v0
	v_mov_b32_e32 v66, v0
	v_mov_b32_e32 v67, v0
	v_mov_b32_e32 v72, v0
	v_mov_b32_e32 v73, v0
	v_mov_b32_e32 v74, v0
	v_mov_b32_e32 v75, v0
	v_mov_b32_e32 v80, v0
	v_mov_b32_e32 v81, v0
	v_mov_b32_e32 v82, v0
	v_mov_b32_e32 v83, v0
	v_mov_b32_e32 v88, v0
	v_mov_b32_e32 v89, v0
	v_mov_b32_e32 v90, v0
	v_mov_b32_e32 v91, v0
	v_mov_b32_e32 v96, v0
	v_mov_b32_e32 v97, v0
	v_mov_b32_e32 v98, v0
	v_mov_b32_e32 v99, v0
	v_mov_b32_e32 v104, v0
	v_mov_b32_e32 v105, v0
	v_mov_b32_e32 v106, v0
	v_mov_b32_e32 v107, v0
	v_mov_b32_e32 v112, v0
	v_mov_b32_e32 v113, v0
	v_mov_b32_e32 v114, v0
	v_mov_b32_e32 v115, v0
	v_mov_b32_e32 v120, v0
	v_mov_b32_e32 v121, v0
	v_mov_b32_e32 v122, v0
	v_mov_b32_e32 v123, v0
	v_mov_b32_e32 v68, v0
	v_mov_b32_e32 v69, v0
	v_mov_b32_e32 v70, v0
	v_mov_b32_e32 v71, v0
	v_mov_b32_e32 v76, v0
	v_mov_b32_e32 v77, v0
	v_mov_b32_e32 v78, v0
	v_mov_b32_e32 v79, v0
	v_mov_b32_e32 v84, v0
	v_mov_b32_e32 v85, v0
	v_mov_b32_e32 v86, v0
	v_mov_b32_e32 v87, v0
	v_mov_b32_e32 v92, v0
	v_mov_b32_e32 v93, v0
	v_mov_b32_e32 v94, v0
	v_mov_b32_e32 v95, v0
	v_mov_b32_e32 v100, v0
	v_mov_b32_e32 v101, v0
	v_mov_b32_e32 v102, v0
	v_mov_b32_e32 v103, v0
	v_mov_b32_e32 v108, v0
	v_mov_b32_e32 v109, v0
	v_mov_b32_e32 v110, v0
	v_mov_b32_e32 v111, v0
	v_mov_b32_e32 v116, v0
	v_mov_b32_e32 v117, v0
	v_mov_b32_e32 v118, v0
	v_mov_b32_e32 v119, v0
	v_mov_b32_e32 v124, v0
	v_mov_b32_e32 v125, v0
	v_mov_b32_e32 v126, v0
	v_mov_b32_e32 v127, v0
	s_mov_b64 s[74:75], 0x80
	v_add_u32_e32 v234, 0x10000, v141
	v_add_u32_e32 v235, 0x14000, v141
	v_add_u32_e32 v236, 0x18000, v141
	v_add_u32_e32 v237, 0x1c000, v141
	s_cmpk_ge_u32 s47, 0x100
	s_cbranch_scc0 .Lmy_pr_2
	s_setprio 1
.Lmy_pr_2:
.LBB0_1510:
	s_add_u32 s98, s14, 0xfff80000
	s_addc_u32 s99, s15, -1
	s_mov_b32 m0, s25
	s_nop 0
	global_load_lds_dwordx4 v136, s[98:99]
	s_mov_b32 m0, s26
	s_nop 0
	global_load_lds_dwordx4 v134, s[98:99]
	s_add_u32 s16, s14, 0xfff80080
	s_addc_u32 s17, s15, -1
	s_add_i32 s36, 0, 0x10000
	s_cmp_eq_u32 s35, 28
	s_cselect_b32 s19, s9, s17
	s_cselect_b32 s18, s30, s16
	s_cselect_b32 s17, s7, s34
	s_cselect_b32 s16, s31, s33
	s_add_i32 s40, 0, 0x14000
	ds_read_b128 v[144:147], v234
	ds_read_b128 v[148:151], v234 offset:1024
	ds_read_b128 v[162:165], v234 offset:2048
	ds_read_b128 v[166:169], v234 offset:3072
	ds_read_b128 v[170:173], v235
	ds_read_b128 v[174:177], v235 offset:1024
	ds_read_b128 v[178:181], v235 offset:2048
	ds_read_b128 v[182:185], v235 offset:3072
	s_add_i32 m0, s21, 0xc000
	ds_read_b128 v[186:189], v143
	ds_read_b128 v[190:193], v143 offset:1024
	ds_read_b128 v[194:197], v143 offset:2048
	ds_read_b128 v[198:201], v143 offset:3072
	ds_read_b128 v[202:205], v143 offset:4096
	ds_read_b128 v[214:217], v143 offset:5120
	ds_read_b128 v[218:221], v143 offset:6144
	ds_read_b128 v[222:225], v143 offset:7168
	global_load_lds_dwordx4 v136, s[14:15]
	s_add_i32 m0, s21, 0xe000
	s_nop 0
	global_load_lds_dwordx4 v134, s[14:15]
	s_waitcnt vmcnt(8)
	s_waitcnt lgkmcnt(0)
	s_barrier
	s_waitcnt lgkmcnt(0)
	v_mfma_f32_16x16x32_bf16 v[124:127], v[144:147], v[186:189], v[124:127]
	v_mfma_f32_16x16x32_bf16 v[116:119], v[162:165], v[186:189], v[116:119]
	v_mfma_f32_16x16x32_bf16 v[108:111], v[144:147], v[194:197], v[108:111]
	v_mfma_f32_16x16x32_bf16 v[100:103], v[162:165], v[194:197], v[100:103]
	v_mfma_f32_16x16x32_bf16 v[92:95], v[144:147], v[202:205], v[92:95]
	v_mfma_f32_16x16x32_bf16 v[84:87], v[162:165], v[202:205], v[84:87]
	v_mfma_f32_16x16x32_bf16 v[76:79], v[144:147], v[218:221], v[76:79]
	v_mfma_f32_16x16x32_bf16 v[68:71], v[162:165], v[218:221], v[68:71]
	v_mfma_f32_16x16x32_bf16 v[124:127], v[148:151], v[190:193], v[124:127]
	v_mfma_f32_16x16x32_bf16 v[116:119], v[166:169], v[190:193], v[116:119]
	v_mfma_f32_16x16x32_bf16 v[108:111], v[148:151], v[198:201], v[108:111]
	v_mfma_f32_16x16x32_bf16 v[100:103], v[166:169], v[198:201], v[100:103]
	v_mfma_f32_16x16x32_bf16 v[92:95], v[148:151], v[214:217], v[92:95]
	v_mfma_f32_16x16x32_bf16 v[84:87], v[166:169], v[214:217], v[84:87]
	v_mfma_f32_16x16x32_bf16 v[76:79], v[148:151], v[222:225], v[76:79]
	v_mfma_f32_16x16x32_bf16 v[68:71], v[166:169], v[222:225], v[68:71]
	v_mfma_f32_16x16x32_bf16 v[120:123], v[170:173], v[186:189], v[120:123]
	v_mfma_f32_16x16x32_bf16 v[112:115], v[178:181], v[186:189], v[112:115]
	v_mfma_f32_16x16x32_bf16 v[104:107], v[170:173], v[194:197], v[104:107]
	v_mfma_f32_16x16x32_bf16 v[96:99], v[178:181], v[194:197], v[96:99]
	v_mfma_f32_16x16x32_bf16 v[88:91], v[170:173], v[202:205], v[88:91]
	v_mfma_f32_16x16x32_bf16 v[80:83], v[178:181], v[202:205], v[80:83]
	v_mfma_f32_16x16x32_bf16 v[72:75], v[170:173], v[218:221], v[72:75]
	v_mfma_f32_16x16x32_bf16 v[64:67], v[178:181], v[218:221], v[64:67]
	v_mfma_f32_16x16x32_bf16 v[120:123], v[174:177], v[190:193], v[120:123]
	v_mfma_f32_16x16x32_bf16 v[112:115], v[182:185], v[190:193], v[112:115]
	v_mfma_f32_16x16x32_bf16 v[104:107], v[174:177], v[198:201], v[104:107]
	v_mfma_f32_16x16x32_bf16 v[96:99], v[182:185], v[198:201], v[96:99]
	v_mfma_f32_16x16x32_bf16 v[88:91], v[174:177], v[214:217], v[88:91]
	v_mfma_f32_16x16x32_bf16 v[80:83], v[182:185], v[214:217], v[80:83]
	v_mfma_f32_16x16x32_bf16 v[72:75], v[174:177], v[222:225], v[72:75]
	v_mfma_f32_16x16x32_bf16 v[64:67], v[182:185], v[222:225], v[64:67]
	s_barrier
	s_add_i32 s36, s36, s20
	s_add_u32 s100, s16, 0x80
	s_addc_u32 s101, s17, 0
	s_mov_b32 m0, s36
	ds_read_b128 v[186:189], v143 offset:16384
	ds_read_b128 v[190:193], v143 offset:17408
	ds_read_b128 v[194:197], v143 offset:18432
	ds_read_b128 v[198:201], v143 offset:19456
	ds_read_b128 v[202:205], v143 offset:20480
	ds_read_b128 v[214:217], v143 offset:21504
	ds_read_b128 v[218:221], v143 offset:22528
	ds_read_b128 v[222:225], v143 offset:23552
	global_load_lds_dwordx4 v152, s[16:17]
	s_add_i32 m0, s36, 0x2000
	s_add_u32 s36, s16, 0x80000
	s_addc_u32 s37, s17, 0
	s_add_i32 s40, s40, s20
	global_load_lds_dwordx4 v128, s[16:17]
	s_mov_b32 m0, s40
	s_nop 0
	global_load_lds_dwordx4 v152, s[36:37]
	s_add_i32 m0, s40, 0x2000
	s_nop 0
	global_load_lds_dwordx4 v128, s[36:37]
	s_waitcnt vmcnt(6)
	s_waitcnt lgkmcnt(0)
	s_barrier
	s_waitcnt lgkmcnt(0)
	v_mfma_f32_16x16x32_bf16 v[60:63], v[144:147], v[186:189], v[60:63]
	v_mfma_f32_16x16x32_bf16 v[52:55], v[162:165], v[186:189], v[52:55]
	v_mfma_f32_16x16x32_bf16 v[44:47], v[144:147], v[194:197], v[44:47]
	v_mfma_f32_16x16x32_bf16 v[36:39], v[162:165], v[194:197], v[36:39]
	v_mfma_f32_16x16x32_bf16 v[28:31], v[144:147], v[202:205], v[28:31]
	v_mfma_f32_16x16x32_bf16 v[20:23], v[162:165], v[202:205], v[20:23]
	v_mfma_f32_16x16x32_bf16 v[12:15], v[144:147], v[218:221], v[12:15]
	v_mfma_f32_16x16x32_bf16 v[4:7], v[162:165], v[218:221], v[4:7]
	v_mfma_f32_16x16x32_bf16 v[60:63], v[148:151], v[190:193], v[60:63]
	v_mfma_f32_16x16x32_bf16 v[52:55], v[166:169], v[190:193], v[52:55]
	v_mfma_f32_16x16x32_bf16 v[44:47], v[148:151], v[198:201], v[44:47]
	v_mfma_f32_16x16x32_bf16 v[36:39], v[166:169], v[198:201], v[36:39]
	v_mfma_f32_16x16x32_bf16 v[28:31], v[148:151], v[214:217], v[28:31]
	v_mfma_f32_16x16x32_bf16 v[20:23], v[166:169], v[214:217], v[20:23]
	v_mfma_f32_16x16x32_bf16 v[12:15], v[148:151], v[222:225], v[12:15]
	v_mfma_f32_16x16x32_bf16 v[4:7], v[166:169], v[222:225], v[4:7]
	v_mfma_f32_16x16x32_bf16 v[56:59], v[170:173], v[186:189], v[56:59]
	v_mfma_f32_16x16x32_bf16 v[48:51], v[178:181], v[186:189], v[48:51]
	v_mfma_f32_16x16x32_bf16 v[40:43], v[170:173], v[194:197], v[40:43]
	v_mfma_f32_16x16x32_bf16 v[32:35], v[178:181], v[194:197], v[32:35]
	v_mfma_f32_16x16x32_bf16 v[24:27], v[170:173], v[202:205], v[24:27]
	v_mfma_f32_16x16x32_bf16 v[16:19], v[178:181], v[202:205], v[16:19]
	v_mfma_f32_16x16x32_bf16 v[8:11], v[170:173], v[218:221], v[8:11]
	v_mfma_f32_16x16x32_bf16 v[0:3], v[178:181], v[218:221], v[0:3]
	v_mfma_f32_16x16x32_bf16 v[56:59], v[174:177], v[190:193], v[56:59]
	v_mfma_f32_16x16x32_bf16 v[48:51], v[182:185], v[190:193], v[48:51]
	v_mfma_f32_16x16x32_bf16 v[40:43], v[174:177], v[198:201], v[40:43]
	v_mfma_f32_16x16x32_bf16 v[32:35], v[182:185], v[198:201], v[32:35]
	v_mfma_f32_16x16x32_bf16 v[24:27], v[174:177], v[214:217], v[24:27]
	v_mfma_f32_16x16x32_bf16 v[16:19], v[182:185], v[214:217], v[16:19]
	v_mfma_f32_16x16x32_bf16 v[8:11], v[174:177], v[222:225], v[8:11]
	v_mfma_f32_16x16x32_bf16 v[0:3], v[182:185], v[222:225], v[0:3]
	s_barrier
	s_mov_b32 m0, s21
	s_nop 0
	global_load_lds_dwordx4 v132, s[18:19]
	s_mov_b32 m0, s22
	s_nop 0
	global_load_lds_dwordx4 v130, s[18:19]
	s_add_i32 s36, 0, 0x18000
	s_add_i32 s37, 0, 0x1c000
	ds_read_b128 v[144:147], v236
	ds_read_b128 v[148:151], v236 offset:1024
	ds_read_b128 v[162:165], v236 offset:2048
	ds_read_b128 v[166:169], v236 offset:3072
	ds_read_b128 v[170:173], v237
	ds_read_b128 v[174:177], v237 offset:1024
	ds_read_b128 v[178:181], v237 offset:2048
	ds_read_b128 v[182:185], v237 offset:3072
	s_add_u32 s18, s18, 0x80000
	s_addc_u32 s19, s19, 0
	s_mov_b32 m0, s23
	ds_read_b128 v[186:189], v143 offset:32768
	ds_read_b128 v[190:193], v143 offset:33792
	ds_read_b128 v[194:197], v143 offset:34816
	ds_read_b128 v[198:201], v143 offset:35840
	ds_read_b128 v[202:205], v143 offset:36864
	ds_read_b128 v[214:217], v143 offset:37888
	ds_read_b128 v[218:221], v143 offset:38912
	ds_read_b128 v[222:225], v143 offset:39936
	global_load_lds_dwordx4 v132, s[18:19]
	s_mov_b32 m0, s24
	s_nop 0
	global_load_lds_dwordx4 v130, s[18:19]
	s_waitcnt vmcnt(8)
	s_waitcnt lgkmcnt(0)
	s_barrier
	s_waitcnt lgkmcnt(0)
	v_mfma_f32_16x16x32_bf16 v[124:127], v[144:147], v[186:189], v[124:127]
	v_mfma_f32_16x16x32_bf16 v[116:119], v[162:165], v[186:189], v[116:119]
	v_mfma_f32_16x16x32_bf16 v[108:111], v[144:147], v[194:197], v[108:111]
	v_mfma_f32_16x16x32_bf16 v[100:103], v[162:165], v[194:197], v[100:103]
	v_mfma_f32_16x16x32_bf16 v[92:95], v[144:147], v[202:205], v[92:95]
	v_mfma_f32_16x16x32_bf16 v[84:87], v[162:165], v[202:205], v[84:87]
	v_mfma_f32_16x16x32_bf16 v[76:79], v[144:147], v[218:221], v[76:79]
	v_mfma_f32_16x16x32_bf16 v[68:71], v[162:165], v[218:221], v[68:71]
	v_mfma_f32_16x16x32_bf16 v[124:127], v[148:151], v[190:193], v[124:127]
	v_mfma_f32_16x16x32_bf16 v[116:119], v[166:169], v[190:193], v[116:119]
	v_mfma_f32_16x16x32_bf16 v[108:111], v[148:151], v[198:201], v[108:111]
	v_mfma_f32_16x16x32_bf16 v[100:103], v[166:169], v[198:201], v[100:103]
	v_mfma_f32_16x16x32_bf16 v[92:95], v[148:151], v[214:217], v[92:95]
	v_mfma_f32_16x16x32_bf16 v[84:87], v[166:169], v[214:217], v[84:87]
	v_mfma_f32_16x16x32_bf16 v[76:79], v[148:151], v[222:225], v[76:79]
	v_mfma_f32_16x16x32_bf16 v[68:71], v[166:169], v[222:225], v[68:71]
	v_mfma_f32_16x16x32_bf16 v[120:123], v[170:173], v[186:189], v[120:123]
	v_mfma_f32_16x16x32_bf16 v[112:115], v[178:181], v[186:189], v[112:115]
	v_mfma_f32_16x16x32_bf16 v[104:107], v[170:173], v[194:197], v[104:107]
	v_mfma_f32_16x16x32_bf16 v[96:99], v[178:181], v[194:197], v[96:99]
	v_mfma_f32_16x16x32_bf16 v[88:91], v[170:173], v[202:205], v[88:91]
	v_mfma_f32_16x16x32_bf16 v[80:83], v[178:181], v[202:205], v[80:83]
	v_mfma_f32_16x16x32_bf16 v[72:75], v[170:173], v[218:221], v[72:75]
	v_mfma_f32_16x16x32_bf16 v[64:67], v[178:181], v[218:221], v[64:67]
	v_mfma_f32_16x16x32_bf16 v[120:123], v[174:177], v[190:193], v[120:123]
	v_mfma_f32_16x16x32_bf16 v[112:115], v[182:185], v[190:193], v[112:115]
	v_mfma_f32_16x16x32_bf16 v[104:107], v[174:177], v[198:201], v[104:107]
	v_mfma_f32_16x16x32_bf16 v[96:99], v[182:185], v[198:201], v[96:99]
	v_mfma_f32_16x16x32_bf16 v[88:91], v[174:177], v[214:217], v[88:91]
	v_mfma_f32_16x16x32_bf16 v[80:83], v[182:185], v[214:217], v[80:83]
	v_mfma_f32_16x16x32_bf16 v[72:75], v[174:177], v[222:225], v[72:75]
	v_mfma_f32_16x16x32_bf16 v[64:67], v[182:185], v[222:225], v[64:67]
	s_barrier
	s_add_i32 s18, s36, s20
	s_mov_b32 m0, s18
	ds_read_b128 v[186:189], v143 offset:49152
	ds_read_b128 v[190:193], v143 offset:50176
	ds_read_b128 v[194:197], v143 offset:51200
	ds_read_b128 v[198:201], v143 offset:52224
	ds_read_b128 v[202:205], v143 offset:53248
	ds_read_b128 v[214:217], v143 offset:54272
	ds_read_b128 v[218:221], v143 offset:55296
	ds_read_b128 v[222:225], v143 offset:56320
	global_load_lds_dwordx4 v152, s[100:101]
	s_add_i32 m0, s18, 0x2000
	s_add_u32 s16, s16, 0x80080
	s_addc_u32 s17, s17, 0
	s_add_i32 s18, s37, s20
	global_load_lds_dwordx4 v128, s[100:101]
	s_mov_b32 m0, s18
	s_nop 0
	global_load_lds_dwordx4 v152, s[16:17]
	s_add_i32 m0, s18, 0x2000
	s_nop 0
	global_load_lds_dwordx4 v128, s[16:17]
	s_waitcnt vmcnt(6)
	s_waitcnt lgkmcnt(0)
	s_barrier
	s_waitcnt lgkmcnt(0)
	v_mfma_f32_16x16x32_bf16 v[60:63], v[144:147], v[186:189], v[60:63]
	v_mfma_f32_16x16x32_bf16 v[52:55], v[162:165], v[186:189], v[52:55]
	v_mfma_f32_16x16x32_bf16 v[44:47], v[144:147], v[194:197], v[44:47]
	v_mfma_f32_16x16x32_bf16 v[36:39], v[162:165], v[194:197], v[36:39]
	v_mfma_f32_16x16x32_bf16 v[28:31], v[144:147], v[202:205], v[28:31]
	v_mfma_f32_16x16x32_bf16 v[20:23], v[162:165], v[202:205], v[20:23]
	v_mfma_f32_16x16x32_bf16 v[12:15], v[144:147], v[218:221], v[12:15]
	v_mfma_f32_16x16x32_bf16 v[4:7], v[162:165], v[218:221], v[4:7]
	v_mfma_f32_16x16x32_bf16 v[60:63], v[148:151], v[190:193], v[60:63]
	v_mfma_f32_16x16x32_bf16 v[52:55], v[166:169], v[190:193], v[52:55]
	v_mfma_f32_16x16x32_bf16 v[44:47], v[148:151], v[198:201], v[44:47]
	v_mfma_f32_16x16x32_bf16 v[36:39], v[166:169], v[198:201], v[36:39]
	v_mfma_f32_16x16x32_bf16 v[28:31], v[148:151], v[214:217], v[28:31]
	v_mfma_f32_16x16x32_bf16 v[20:23], v[166:169], v[214:217], v[20:23]
	v_mfma_f32_16x16x32_bf16 v[12:15], v[148:151], v[222:225], v[12:15]
	v_mfma_f32_16x16x32_bf16 v[4:7], v[166:169], v[222:225], v[4:7]
	v_mfma_f32_16x16x32_bf16 v[56:59], v[170:173], v[186:189], v[56:59]
	v_mfma_f32_16x16x32_bf16 v[48:51], v[178:181], v[186:189], v[48:51]
	v_mfma_f32_16x16x32_bf16 v[40:43], v[170:173], v[194:197], v[40:43]
	v_mfma_f32_16x16x32_bf16 v[32:35], v[178:181], v[194:197], v[32:35]
	v_mfma_f32_16x16x32_bf16 v[24:27], v[170:173], v[202:205], v[24:27]
	v_mfma_f32_16x16x32_bf16 v[16:19], v[178:181], v[202:205], v[16:19]
	v_mfma_f32_16x16x32_bf16 v[8:11], v[170:173], v[218:221], v[8:11]
	v_mfma_f32_16x16x32_bf16 v[0:3], v[178:181], v[218:221], v[0:3]
	v_mfma_f32_16x16x32_bf16 v[56:59], v[174:177], v[190:193], v[56:59]
	v_mfma_f32_16x16x32_bf16 v[48:51], v[182:185], v[190:193], v[48:51]
	v_mfma_f32_16x16x32_bf16 v[40:43], v[174:177], v[198:201], v[40:43]
	v_mfma_f32_16x16x32_bf16 v[32:35], v[182:185], v[198:201], v[32:35]
	v_mfma_f32_16x16x32_bf16 v[24:27], v[174:177], v[214:217], v[24:27]
	v_mfma_f32_16x16x32_bf16 v[16:19], v[182:185], v[214:217], v[16:19]
	v_mfma_f32_16x16x32_bf16 v[8:11], v[174:177], v[222:225], v[8:11]
	v_mfma_f32_16x16x32_bf16 v[0:3], v[182:185], v[222:225], v[0:3]
	s_barrier
	s_add_i32 s35, s35, 2
	s_add_u32 s33, s33, 0x100
	s_addc_u32 s34, s34, 0
	s_add_u32 s14, s14, 0x100
	s_addc_u32 s15, s15, 0
	s_cmp_gt_u32 s35, 29
	s_cbranch_scc0 .LBB0_1510
	s_setprio 0
	s_and_b64 vcc, exec, s[4:5]
	s_cbranch_vccz .LBB0_1513
	s_barrier

.LBB0_1589:
	s_add_u32 s30, s12, 0x100
	v_mov_b32_e32 v0, 0
	s_addc_u32 s31, s13, 0
	s_mov_b32 s33, -2
	v_mov_b32_e32 v1, v0
	v_mov_b32_e32 v2, v0
	v_mov_b32_e32 v3, v0
	v_mov_b32_e32 v4, v0
	v_mov_b32_e32 v5, v0
	v_mov_b32_e32 v6, v0
	v_mov_b32_e32 v7, v0
	v_mov_b32_e32 v16, v0
	v_mov_b32_e32 v17, v0
	v_mov_b32_e32 v18, v0
	v_mov_b32_e32 v19, v0
	v_mov_b32_e32 v20, v0
	v_mov_b32_e32 v21, v0
	v_mov_b32_e32 v22, v0
	v_mov_b32_e32 v23, v0
	v_mov_b32_e32 v32, v0
	v_mov_b32_e32 v33, v0
	v_mov_b32_e32 v34, v0
	v_mov_b32_e32 v35, v0
	v_mov_b32_e32 v36, v0
	v_mov_b32_e32 v37, v0
	v_mov_b32_e32 v38, v0
	v_mov_b32_e32 v39, v0
	v_mov_b32_e32 v48, v0
	v_mov_b32_e32 v49, v0
	v_mov_b32_e32 v50, v0
	v_mov_b32_e32 v51, v0
	v_mov_b32_e32 v52, v0
	v_mov_b32_e32 v53, v0
	v_mov_b32_e32 v54, v0
	v_mov_b32_e32 v55, v0
	v_mov_b32_e32 v8, v0
	v_mov_b32_e32 v9, v0
	v_mov_b32_e32 v10, v0
	v_mov_b32_e32 v11, v0
	v_mov_b32_e32 v12, v0
	v_mov_b32_e32 v13, v0
	v_mov_b32_e32 v14, v0
	v_mov_b32_e32 v15, v0
	v_mov_b32_e32 v24, v0
	v_mov_b32_e32 v25, v0
	v_mov_b32_e32 v26, v0
	v_mov_b32_e32 v27, v0
	v_mov_b32_e32 v28, v0
	v_mov_b32_e32 v29, v0
	v_mov_b32_e32 v30, v0
	v_mov_b32_e32 v31, v0
	v_mov_b32_e32 v40, v0
	v_mov_b32_e32 v41, v0
	v_mov_b32_e32 v42, v0
	v_mov_b32_e32 v43, v0
	v_mov_b32_e32 v44, v0
	v_mov_b32_e32 v45, v0
	v_mov_b32_e32 v46, v0
	v_mov_b32_e32 v47, v0
	v_mov_b32_e32 v56, v0
	v_mov_b32_e32 v57, v0
	v_mov_b32_e32 v58, v0
	v_mov_b32_e32 v59, v0
	v_mov_b32_e32 v60, v0
	v_mov_b32_e32 v61, v0
	v_mov_b32_e32 v62, v0
	v_mov_b32_e32 v63, v0
	v_mov_b32_e32 v64, v0
	v_mov_b32_e32 v65, v0
	v_mov_b32_e32 v66, v0
	v_mov_b32_e32 v67, v0
	v_mov_b32_e32 v68, v0
	v_mov_b32_e32 v69, v0
	v_mov_b32_e32 v70, v0
	v_mov_b32_e32 v71, v0
	v_mov_b32_e32 v80, v0
	v_mov_b32_e32 v81, v0
	v_mov_b32_e32 v82, v0
	v_mov_b32_e32 v83, v0
	v_mov_b32_e32 v84, v0
	v_mov_b32_e32 v85, v0
	v_mov_b32_e32 v86, v0
	v_mov_b32_e32 v87, v0
	v_mov_b32_e32 v96, v0
	v_mov_b32_e32 v97, v0
	v_mov_b32_e32 v98, v0
	v_mov_b32_e32 v99, v0
	v_mov_b32_e32 v100, v0
	v_mov_b32_e32 v101, v0
	v_mov_b32_e32 v102, v0
	v_mov_b32_e32 v103, v0
	v_mov_b32_e32 v112, v0
	v_mov_b32_e32 v113, v0
	v_mov_b32_e32 v114, v0
	v_mov_b32_e32 v115, v0
	v_mov_b32_e32 v116, v0
	v_mov_b32_e32 v117, v0
	v_mov_b32_e32 v118, v0
	v_mov_b32_e32 v119, v0
	v_mov_b32_e32 v72, v0
	v_mov_b32_e32 v73, v0
	v_mov_b32_e32 v74, v0
	v_mov_b32_e32 v75, v0
	v_mov_b32_e32 v76, v0
	v_mov_b32_e32 v77, v0
	v_mov_b32_e32 v78, v0
	v_mov_b32_e32 v79, v0
	v_mov_b32_e32 v88, v0
	v_mov_b32_e32 v89, v0
	v_mov_b32_e32 v90, v0
	v_mov_b32_e32 v91, v0
	v_mov_b32_e32 v92, v0
	v_mov_b32_e32 v93, v0
	v_mov_b32_e32 v94, v0
	v_mov_b32_e32 v95, v0
	v_mov_b32_e32 v104, v0
	v_mov_b32_e32 v105, v0
	v_mov_b32_e32 v106, v0
	v_mov_b32_e32 v107, v0
	v_mov_b32_e32 v108, v0
	v_mov_b32_e32 v109, v0
	v_mov_b32_e32 v110, v0
	v_mov_b32_e32 v111, v0
	v_mov_b32_e32 v120, v0
	v_mov_b32_e32 v121, v0
	v_mov_b32_e32 v122, v0
	v_mov_b32_e32 v123, v0
	v_mov_b32_e32 v124, v0
	v_mov_b32_e32 v125, v0
	v_mov_b32_e32 v126, v0
	v_mov_b32_e32 v127, v0
	s_mov_b64 s[36:37], 0x80
	s_waitcnt vmcnt(0)
	v_add_u32_e32 v234, 0x10000, v141
	v_add_u32_e32 v235, 0x14000, v141
	v_add_u32_e32 v236, 0x18000, v141
	v_add_u32_e32 v237, 0x1c000, v141
	s_cmpk_ge_u32 s47, 0x100
	s_cbranch_scc0 .Lmy_pr_3
	s_setprio 1
.Lmy_pr_3:
.LBB0_1590:
	s_add_u32 s98, s10, 0xffea0000
	s_addc_u32 s99, s11, -1
	s_mov_b32 m0, s23
	s_nop 0
	global_load_lds_dwordx4 v132, s[98:99]
	s_mov_b32 m0, s24
	s_nop 0
	global_load_lds_dwordx4 v130, s[98:99]
	s_add_u32 s12, s10, 0x100
	s_addc_u32 s13, s11, 0
	s_add_i32 s34, 0, 0x10000
	s_cmpk_eq_i32 s33, 0x54
	s_cselect_b32 s17, s3, s13
	s_cselect_b32 s16, s2, s12
	s_cselect_b32 s15, s9, s31
	s_cselect_b32 s14, s8, s30
	s_add_i32 s35, 0, 0x14000
	ds_read_b128 v[134:137], v234
	ds_read_b128 v[144:147], v234 offset:1024
	ds_read_b128 v[148:151], v234 offset:2048
	ds_read_b128 v[162:165], v234 offset:3072
	ds_read_b128 v[166:169], v235
	ds_read_b128 v[170:173], v235 offset:1024
	ds_read_b128 v[174:177], v235 offset:2048
	ds_read_b128 v[178:181], v235 offset:3072
	s_add_i32 m0, s19, 0xc000
	ds_read_b128 v[182:185], v143
	ds_read_b128 v[186:189], v143 offset:1024
	ds_read_b128 v[190:193], v143 offset:2048
	ds_read_b128 v[194:197], v143 offset:3072
	ds_read_b128 v[198:201], v143 offset:4096
	ds_read_b128 v[202:205], v143 offset:5120
	ds_read_b128 v[214:217], v143 offset:6144
	ds_read_b128 v[218:221], v143 offset:7168
	global_load_lds_dwordx4 v132, s[10:11]
	s_add_i32 m0, s19, 0xe000
	s_nop 0
	global_load_lds_dwordx4 v130, s[10:11]
	s_waitcnt vmcnt(8)
	s_waitcnt lgkmcnt(0)
	s_barrier
	s_waitcnt lgkmcnt(0)
	v_mfma_f32_16x16x32_bf16 v[124:127], v[134:137], v[182:185], v[124:127]
	v_mfma_f32_16x16x32_bf16 v[120:123], v[148:151], v[182:185], v[120:123]
	v_mfma_f32_16x16x32_bf16 v[108:111], v[134:137], v[190:193], v[108:111]
	v_mfma_f32_16x16x32_bf16 v[104:107], v[148:151], v[190:193], v[104:107]
	v_mfma_f32_16x16x32_bf16 v[92:95], v[134:137], v[198:201], v[92:95]
	v_mfma_f32_16x16x32_bf16 v[88:91], v[148:151], v[198:201], v[88:91]
	v_mfma_f32_16x16x32_bf16 v[76:79], v[134:137], v[214:217], v[76:79]
	v_mfma_f32_16x16x32_bf16 v[72:75], v[148:151], v[214:217], v[72:75]
	v_mfma_f32_16x16x32_bf16 v[124:127], v[144:147], v[186:189], v[124:127]
	v_mfma_f32_16x16x32_bf16 v[120:123], v[162:165], v[186:189], v[120:123]
	v_mfma_f32_16x16x32_bf16 v[108:111], v[144:147], v[194:197], v[108:111]
	v_mfma_f32_16x16x32_bf16 v[104:107], v[162:165], v[194:197], v[104:107]
	v_mfma_f32_16x16x32_bf16 v[92:95], v[144:147], v[202:205], v[92:95]
	v_mfma_f32_16x16x32_bf16 v[88:91], v[162:165], v[202:205], v[88:91]
	v_mfma_f32_16x16x32_bf16 v[76:79], v[144:147], v[218:221], v[76:79]
	v_mfma_f32_16x16x32_bf16 v[72:75], v[162:165], v[218:221], v[72:75]
	v_mfma_f32_16x16x32_bf16 v[116:119], v[166:169], v[182:185], v[116:119]
	v_mfma_f32_16x16x32_bf16 v[112:115], v[174:177], v[182:185], v[112:115]
	v_mfma_f32_16x16x32_bf16 v[100:103], v[166:169], v[190:193], v[100:103]
	v_mfma_f32_16x16x32_bf16 v[96:99], v[174:177], v[190:193], v[96:99]
	v_mfma_f32_16x16x32_bf16 v[84:87], v[166:169], v[198:201], v[84:87]
	v_mfma_f32_16x16x32_bf16 v[80:83], v[174:177], v[198:201], v[80:83]
	v_mfma_f32_16x16x32_bf16 v[68:71], v[166:169], v[214:217], v[68:71]
	v_mfma_f32_16x16x32_bf16 v[64:67], v[174:177], v[214:217], v[64:67]
	v_mfma_f32_16x16x32_bf16 v[116:119], v[170:173], v[186:189], v[116:119]
	v_mfma_f32_16x16x32_bf16 v[112:115], v[178:181], v[186:189], v[112:115]
	v_mfma_f32_16x16x32_bf16 v[100:103], v[170:173], v[194:197], v[100:103]
	v_mfma_f32_16x16x32_bf16 v[96:99], v[178:181], v[194:197], v[96:99]
	v_mfma_f32_16x16x32_bf16 v[84:87], v[170:173], v[202:205], v[84:87]
	v_mfma_f32_16x16x32_bf16 v[80:83], v[178:181], v[202:205], v[80:83]
	v_mfma_f32_16x16x32_bf16 v[68:71], v[170:173], v[218:221], v[68:71]
	v_mfma_f32_16x16x32_bf16 v[64:67], v[178:181], v[218:221], v[64:67]
	s_barrier
	s_add_i32 s10, s34, s18
	s_add_u32 s100, s14, 0x80
	s_addc_u32 s101, s15, 0
	s_mov_b32 m0, s10
	ds_read_b128 v[182:185], v143 offset:16384
	ds_read_b128 v[186:189], v143 offset:17408
	ds_read_b128 v[190:193], v143 offset:18432
	ds_read_b128 v[194:197], v143 offset:19456
	ds_read_b128 v[198:201], v143 offset:20480
	ds_read_b128 v[202:205], v143 offset:21504
	ds_read_b128 v[214:217], v143 offset:22528
	ds_read_b128 v[218:221], v143 offset:23552
	global_load_lds_dwordx4 v152, s[14:15]
	s_add_i32 m0, s10, 0x2000
	s_add_u32 s10, s14, 0x160000
	s_addc_u32 s11, s15, 0
	s_add_i32 s34, s35, s18
	global_load_lds_dwordx4 v128, s[14:15]
	s_mov_b32 m0, s34
	s_nop 0
	global_load_lds_dwordx4 v152, s[10:11]
	s_add_i32 m0, s34, 0x2000
	s_nop 0
	global_load_lds_dwordx4 v128, s[10:11]
	s_waitcnt vmcnt(6)
	s_waitcnt lgkmcnt(0)
	s_barrier
	s_waitcnt lgkmcnt(0)
	v_mfma_f32_16x16x32_bf16 v[60:63], v[134:137], v[182:185], v[60:63]
	v_mfma_f32_16x16x32_bf16 v[56:59], v[148:151], v[182:185], v[56:59]
	v_mfma_f32_16x16x32_bf16 v[44:47], v[134:137], v[190:193], v[44:47]
	v_mfma_f32_16x16x32_bf16 v[40:43], v[148:151], v[190:193], v[40:43]
	v_mfma_f32_16x16x32_bf16 v[28:31], v[134:137], v[198:201], v[28:31]
	v_mfma_f32_16x16x32_bf16 v[24:27], v[148:151], v[198:201], v[24:27]
	v_mfma_f32_16x16x32_bf16 v[12:15], v[134:137], v[214:217], v[12:15]
	v_mfma_f32_16x16x32_bf16 v[8:11], v[148:151], v[214:217], v[8:11]
	v_mfma_f32_16x16x32_bf16 v[60:63], v[144:147], v[186:189], v[60:63]
	v_mfma_f32_16x16x32_bf16 v[56:59], v[162:165], v[186:189], v[56:59]
	v_mfma_f32_16x16x32_bf16 v[44:47], v[144:147], v[194:197], v[44:47]
	v_mfma_f32_16x16x32_bf16 v[40:43], v[162:165], v[194:197], v[40:43]
	v_mfma_f32_16x16x32_bf16 v[28:31], v[144:147], v[202:205], v[28:31]
	v_mfma_f32_16x16x32_bf16 v[24:27], v[162:165], v[202:205], v[24:27]
	v_mfma_f32_16x16x32_bf16 v[12:15], v[144:147], v[218:221], v[12:15]
	v_mfma_f32_16x16x32_bf16 v[8:11], v[162:165], v[218:221], v[8:11]
	v_mfma_f32_16x16x32_bf16 v[52:55], v[166:169], v[182:185], v[52:55]
	v_mfma_f32_16x16x32_bf16 v[48:51], v[174:177], v[182:185], v[48:51]
	v_mfma_f32_16x16x32_bf16 v[36:39], v[166:169], v[190:193], v[36:39]
	v_mfma_f32_16x16x32_bf16 v[32:35], v[174:177], v[190:193], v[32:35]
	v_mfma_f32_16x16x32_bf16 v[20:23], v[166:169], v[198:201], v[20:23]
	v_mfma_f32_16x16x32_bf16 v[16:19], v[174:177], v[198:201], v[16:19]
	v_mfma_f32_16x16x32_bf16 v[4:7], v[166:169], v[214:217], v[4:7]
	v_mfma_f32_16x16x32_bf16 v[0:3], v[174:177], v[214:217], v[0:3]
	v_mfma_f32_16x16x32_bf16 v[52:55], v[170:173], v[186:189], v[52:55]
	v_mfma_f32_16x16x32_bf16 v[48:51], v[178:181], v[186:189], v[48:51]
	v_mfma_f32_16x16x32_bf16 v[36:39], v[170:173], v[194:197], v[36:39]
	v_mfma_f32_16x16x32_bf16 v[32:35], v[178:181], v[194:197], v[32:35]
	v_mfma_f32_16x16x32_bf16 v[20:23], v[170:173], v[202:205], v[20:23]
	v_mfma_f32_16x16x32_bf16 v[16:19], v[178:181], v[202:205], v[16:19]
	v_mfma_f32_16x16x32_bf16 v[4:7], v[170:173], v[218:221], v[4:7]
	v_mfma_f32_16x16x32_bf16 v[0:3], v[178:181], v[218:221], v[0:3]
	s_barrier
	s_mov_b32 m0, s19
	s_nop 0
	global_load_lds_dwordx4 v152, s[16:17]
	s_mov_b32 m0, s20
	s_nop 0
	global_load_lds_dwordx4 v128, s[16:17]
	s_add_i32 s34, 0, 0x18000
	s_add_i32 s35, 0, 0x1c000
	ds_read_b128 v[134:137], v236
	ds_read_b128 v[144:147], v236 offset:1024
	ds_read_b128 v[148:151], v236 offset:2048
	ds_read_b128 v[162:165], v236 offset:3072
	ds_read_b128 v[166:169], v237
	ds_read_b128 v[170:173], v237 offset:1024
	ds_read_b128 v[174:177], v237 offset:2048
	ds_read_b128 v[178:181], v237 offset:3072
	s_add_u32 s10, s16, 0x160000
	s_addc_u32 s11, s17, 0
	s_mov_b32 m0, s21
	ds_read_b128 v[182:185], v143 offset:32768
	ds_read_b128 v[186:189], v143 offset:33792
	ds_read_b128 v[190:193], v143 offset:34816
	ds_read_b128 v[194:197], v143 offset:35840
	ds_read_b128 v[198:201], v143 offset:36864
	ds_read_b128 v[202:205], v143 offset:37888
	ds_read_b128 v[214:217], v143 offset:38912
	ds_read_b128 v[218:221], v143 offset:39936
	global_load_lds_dwordx4 v152, s[10:11]
	s_mov_b32 m0, s22
	s_nop 0
	global_load_lds_dwordx4 v128, s[10:11]
	s_waitcnt vmcnt(8)
	s_waitcnt lgkmcnt(0)
	s_barrier
	s_waitcnt lgkmcnt(0)
	v_mfma_f32_16x16x32_bf16 v[124:127], v[134:137], v[182:185], v[124:127]
	v_mfma_f32_16x16x32_bf16 v[120:123], v[148:151], v[182:185], v[120:123]
	v_mfma_f32_16x16x32_bf16 v[108:111], v[134:137], v[190:193], v[108:111]
	v_mfma_f32_16x16x32_bf16 v[104:107], v[148:151], v[190:193], v[104:107]
	v_mfma_f32_16x16x32_bf16 v[92:95], v[134:137], v[198:201], v[92:95]
	v_mfma_f32_16x16x32_bf16 v[88:91], v[148:151], v[198:201], v[88:91]
	v_mfma_f32_16x16x32_bf16 v[76:79], v[134:137], v[214:217], v[76:79]
	v_mfma_f32_16x16x32_bf16 v[72:75], v[148:151], v[214:217], v[72:75]
	v_mfma_f32_16x16x32_bf16 v[124:127], v[144:147], v[186:189], v[124:127]
	v_mfma_f32_16x16x32_bf16 v[120:123], v[162:165], v[186:189], v[120:123]
	v_mfma_f32_16x16x32_bf16 v[108:111], v[144:147], v[194:197], v[108:111]
	v_mfma_f32_16x16x32_bf16 v[104:107], v[162:165], v[194:197], v[104:107]
	v_mfma_f32_16x16x32_bf16 v[92:95], v[144:147], v[202:205], v[92:95]
	v_mfma_f32_16x16x32_bf16 v[88:91], v[162:165], v[202:205], v[88:91]
	v_mfma_f32_16x16x32_bf16 v[76:79], v[144:147], v[218:221], v[76:79]
	v_mfma_f32_16x16x32_bf16 v[72:75], v[162:165], v[218:221], v[72:75]
	v_mfma_f32_16x16x32_bf16 v[116:119], v[166:169], v[182:185], v[116:119]
	v_mfma_f32_16x16x32_bf16 v[112:115], v[174:177], v[182:185], v[112:115]
	v_mfma_f32_16x16x32_bf16 v[100:103], v[166:169], v[190:193], v[100:103]
	v_mfma_f32_16x16x32_bf16 v[96:99], v[174:177], v[190:193], v[96:99]
	v_mfma_f32_16x16x32_bf16 v[84:87], v[166:169], v[198:201], v[84:87]
	v_mfma_f32_16x16x32_bf16 v[80:83], v[174:177], v[198:201], v[80:83]
	v_mfma_f32_16x16x32_bf16 v[68:71], v[166:169], v[214:217], v[68:71]
	v_mfma_f32_16x16x32_bf16 v[64:67], v[174:177], v[214:217], v[64:67]
	v_mfma_f32_16x16x32_bf16 v[116:119], v[170:173], v[186:189], v[116:119]
	v_mfma_f32_16x16x32_bf16 v[112:115], v[178:181], v[186:189], v[112:115]
	v_mfma_f32_16x16x32_bf16 v[100:103], v[170:173], v[194:197], v[100:103]
	v_mfma_f32_16x16x32_bf16 v[96:99], v[178:181], v[194:197], v[96:99]
	v_mfma_f32_16x16x32_bf16 v[84:87], v[170:173], v[202:205], v[84:87]
	v_mfma_f32_16x16x32_bf16 v[80:83], v[178:181], v[202:205], v[80:83]
	v_mfma_f32_16x16x32_bf16 v[68:71], v[170:173], v[218:221], v[68:71]
	v_mfma_f32_16x16x32_bf16 v[64:67], v[178:181], v[218:221], v[64:67]
	s_barrier
	s_add_i32 s10, s34, s18
	s_mov_b32 m0, s10
	ds_read_b128 v[182:185], v143 offset:49152
	ds_read_b128 v[186:189], v143 offset:50176
	ds_read_b128 v[190:193], v143 offset:51200
	ds_read_b128 v[194:197], v143 offset:52224
	ds_read_b128 v[198:201], v143 offset:53248
	ds_read_b128 v[202:205], v143 offset:54272
	ds_read_b128 v[214:217], v143 offset:55296
	ds_read_b128 v[218:221], v143 offset:56320
	global_load_lds_dwordx4 v152, s[100:101]
	s_add_i32 m0, s10, 0x2000
	s_add_u32 s10, s14, 0x160080
	s_addc_u32 s11, s15, 0
	s_add_i32 s14, s35, s18
	global_load_lds_dwordx4 v128, s[100:101]
	s_mov_b32 m0, s14
	s_nop 0
	global_load_lds_dwordx4 v152, s[10:11]
	s_add_i32 m0, s14, 0x2000
	s_nop 0
	global_load_lds_dwordx4 v128, s[10:11]
	s_waitcnt vmcnt(6)
	s_waitcnt lgkmcnt(0)
	s_barrier
	s_waitcnt lgkmcnt(0)
	v_mfma_f32_16x16x32_bf16 v[60:63], v[134:137], v[182:185], v[60:63]
	v_mfma_f32_16x16x32_bf16 v[56:59], v[148:151], v[182:185], v[56:59]
	v_mfma_f32_16x16x32_bf16 v[44:47], v[134:137], v[190:193], v[44:47]
	v_mfma_f32_16x16x32_bf16 v[40:43], v[148:151], v[190:193], v[40:43]
	v_mfma_f32_16x16x32_bf16 v[28:31], v[134:137], v[198:201], v[28:31]
	v_mfma_f32_16x16x32_bf16 v[24:27], v[148:151], v[198:201], v[24:27]
	v_mfma_f32_16x16x32_bf16 v[12:15], v[134:137], v[214:217], v[12:15]
	v_mfma_f32_16x16x32_bf16 v[8:11], v[148:151], v[214:217], v[8:11]
	v_mfma_f32_16x16x32_bf16 v[60:63], v[144:147], v[186:189], v[60:63]
	v_mfma_f32_16x16x32_bf16 v[56:59], v[162:165], v[186:189], v[56:59]
	v_mfma_f32_16x16x32_bf16 v[44:47], v[144:147], v[194:197], v[44:47]
	v_mfma_f32_16x16x32_bf16 v[40:43], v[162:165], v[194:197], v[40:43]
	v_mfma_f32_16x16x32_bf16 v[28:31], v[144:147], v[202:205], v[28:31]
	v_mfma_f32_16x16x32_bf16 v[24:27], v[162:165], v[202:205], v[24:27]
	v_mfma_f32_16x16x32_bf16 v[12:15], v[144:147], v[218:221], v[12:15]
	v_mfma_f32_16x16x32_bf16 v[8:11], v[162:165], v[218:221], v[8:11]
	v_mfma_f32_16x16x32_bf16 v[52:55], v[166:169], v[182:185], v[52:55]
	v_mfma_f32_16x16x32_bf16 v[48:51], v[174:177], v[182:185], v[48:51]
	v_mfma_f32_16x16x32_bf16 v[36:39], v[166:169], v[190:193], v[36:39]
	v_mfma_f32_16x16x32_bf16 v[32:35], v[174:177], v[190:193], v[32:35]
	v_mfma_f32_16x16x32_bf16 v[20:23], v[166:169], v[198:201], v[20:23]
	v_mfma_f32_16x16x32_bf16 v[16:19], v[174:177], v[198:201], v[16:19]
	v_mfma_f32_16x16x32_bf16 v[4:7], v[166:169], v[214:217], v[4:7]
	v_mfma_f32_16x16x32_bf16 v[0:3], v[174:177], v[214:217], v[0:3]
	v_mfma_f32_16x16x32_bf16 v[52:55], v[170:173], v[186:189], v[52:55]
	v_mfma_f32_16x16x32_bf16 v[48:51], v[178:181], v[186:189], v[48:51]
	v_mfma_f32_16x16x32_bf16 v[36:39], v[170:173], v[194:197], v[36:39]
	v_mfma_f32_16x16x32_bf16 v[32:35], v[178:181], v[194:197], v[32:35]
	v_mfma_f32_16x16x32_bf16 v[20:23], v[170:173], v[202:205], v[20:23]
	v_mfma_f32_16x16x32_bf16 v[16:19], v[178:181], v[202:205], v[16:19]
	v_mfma_f32_16x16x32_bf16 v[4:7], v[170:173], v[218:221], v[4:7]
	v_mfma_f32_16x16x32_bf16 v[0:3], v[178:181], v[218:221], v[0:3]
	s_barrier
	s_add_i32 s33, s33, 2
	s_add_u32 s30, s30, 0x100
	s_addc_u32 s31, s31, 0
	s_cmpk_gt_u32 s33, 0x55
	s_mov_b64 s[10:11], s[12:13]
	s_cbranch_scc0 .LBB0_1590
	s_setprio 0
	s_and_b64 vcc, exec, s[6:7]
	s_cbranch_vccz .LBB0_1593
	s_barrier
